# phase 1: half of the workgroups run the shift GEMVs before the row norms (HBM-bound and latency-bound work overlap across workgroups)
# speedup vs baseline: 1.0052x; 1.0052x over previous
.LBB0_97:
	s_or_b64 exec, exec, s[38:39]
	s_waitcnt lgkmcnt(0)
	s_barrier
	s_mov_b32 s101, 0
	s_bitcmp1_b32 s2, 3
	s_cbranch_scc0 .Lp1_norm
	s_mov_b32 s101, 1
	s_branch .LBB0_108
.Lp1_norm:
	v_mbcnt_lo_u32_b32 v0, -1, 0
	v_mbcnt_hi_u32_b32 v0, -1, v0
	v_readlane_b32 s1, v253, 47
	v_add_u32_e32 v16, s33, v0
	v_writelane_b32 v253, s80, 54
	v_readfirstlane_b32 s0, v16
	s_ashr_i32 s0, s0, 6
	v_writelane_b32 v253, s81, 55
	s_and_b32 s86, s2, 0xff
	s_add_i32 s4, s0, s1
	v_writelane_b32 v253, s82, 56
	s_cmp_gt_i32 s4, 0x8fff
	v_writelane_b32 v253, s83, 57
	s_cbranch_scc1 .LBB0_108
	v_lshlrev_b32_e32 v0, 2, v16
	v_and_b32_e32 v18, 0xfc, v0
	v_readlane_b32 s8, v253, 10
	v_lshlrev_b32_e32 v12, 2, v18
	v_readlane_b32 s16, v253, 18
	v_readlane_b32 s17, v253, 19
	s_nop 4
	global_load_dwordx4 v[0:3], v12, s[16:17]
	global_load_dwordx4 v[4:7], v12, s[16:17] offset:1024
	global_load_dwordx4 v[8:11], v12, s[16:17] offset:2048
	s_nop 0
	global_load_dwordx4 v[12:15], v12, s[16:17] offset:3072
	v_mbcnt_hi_u32_b32 v17, -1, v51
	v_and_b32_e32 v19, 64, v17
	v_add_u32_e32 v19, 64, v19
	v_xor_b32_e32 v20, 1, v17
	v_cmp_lt_i32_e32 vcc, v20, v19
	s_ashr_i32 s5, s4, 31
	s_lshl_b64 s[6:7], s[4:5], 11
	v_cndmask_b32_e32 v20, v17, v20, vcc
	v_lshlrev_b32_e32 v53, 2, v20
	v_xor_b32_e32 v20, 2, v17
	v_cmp_lt_i32_e32 vcc, v20, v19
	s_add_u32 s6, s62, s6
	s_addc_u32 s7, s63, s7
	v_cndmask_b32_e32 v20, v17, v20, vcc
	v_lshlrev_b32_e32 v55, 2, v20
	v_xor_b32_e32 v20, 4, v17
	v_cmp_lt_i32_e32 vcc, v20, v19
	s_and_b32 s1, s2, 7
	s_lshl_b32 s1, s1, 8
	v_cndmask_b32_e32 v20, v17, v20, vcc
	v_lshlrev_b32_e32 v62, 2, v20
	v_xor_b32_e32 v20, 8, v17
	v_cmp_lt_i32_e32 vcc, v20, v19
	s_add_i32 s0, s0, s1
	v_readlane_b32 s1, v253, 26
	v_cndmask_b32_e32 v20, v17, v20, vcc
	v_lshlrev_b32_e32 v63, 2, v20
	v_xor_b32_e32 v20, 16, v17
	s_lshl_b32 s1, s1, 3
	v_cmp_lt_i32_e32 vcc, v20, v19
	s_add_i32 s0, s0, s1
	s_addk_i32 s0, 0x800
	v_cndmask_b32_e32 v20, v17, v20, vcc
	v_lshlrev_b32_e32 v64, 2, v20
	v_xor_b32_e32 v20, 32, v17
	s_ashr_i32 s1, s0, 31
	v_cmp_lt_i32_e32 vcc, v20, v19
	s_lshl_b64 s[0:1], s[0:1], 11
	v_readlane_b32 s9, v253, 11
	v_readlane_b32 s18, v253, 20
	v_readlane_b32 s19, v253, 21
	v_mov_b32_e32 v49, 0
	v_cndmask_b32_e32 v17, v17, v20, vcc
	v_and_b32_e32 v16, 63, v16
	s_add_u32 s8, s62, s0
	v_lshlrev_b32_e32 v65, 2, v17
	v_or_b32_e32 v50, 0x100, v18
	v_or_b32_e32 v52, 0x200, v18
	v_or_b32_e32 v54, 0x300, v18
	v_lshlrev_b32_e32 v48, 3, v16
	s_addc_u32 s9, s63, s1
	v_lshlrev_b32_e32 v56, 2, v18
	v_mov_b32_e32 v57, v49
	v_mov_b32_e32 v66, 0x358637bd
	s_movk_i32 s18, 0x7fff
	s_mov_b32 s19, 0xffff0000
	v_readlane_b32 s10, v253, 12
	v_readlane_b32 s11, v253, 13
	v_readlane_b32 s12, v253, 14
	v_readlane_b32 s13, v253, 15
	v_readlane_b32 s14, v253, 16
	v_readlane_b32 s15, v253, 17
	v_readlane_b32 s20, v253, 22
	v_readlane_b32 s21, v253, 23
	v_readlane_b32 s22, v253, 24
	v_readlane_b32 s23, v253, 25
	s_branch .LBB0_100
.LBB0_100:
	s_mov_b32 s5, 0
	v_readlane_b32 s0, v253, 10
	v_readlane_b32 s1, v253, 11
	s_lshl_b64 s[16:17], s[4:5], 12
	s_add_u32 s0, s0, s16
	s_addc_u32 s1, s1, s17
	v_readlane_b32 s10, v253, 27
	v_readlane_b32 s11, v253, 28
	s_add_u32 s12, s10, 0x1000
	s_addc_u32 s13, s11, 0
	s_lshl_b64 s[14:15], s[4:5], 11
	s_add_u32 s14, s62, s14
	s_addc_u32 s15, s63, s15
	s_add_u32 s14, s14, 0x6200000
	s_addc_u32 s15, s15, 0
	v_mov_b32_e32 v149, 0
	global_load_dwordx4 v[100:103], v56, s[10:11]
	global_load_dwordx4 v[104:107], v56, s[10:11] offset:1024
	global_load_dwordx4 v[108:111], v56, s[10:11] offset:2048
	global_load_dwordx4 v[112:115], v56, s[10:11] offset:3072
	global_load_dwordx4 v[84:87], v56, s[12:13]
	global_load_dwordx4 v[88:91], v56, s[12:13] offset:1024
	global_load_dwordx4 v[92:95], v56, s[12:13] offset:2048
	global_load_dwordx4 v[96:99], v56, s[12:13] offset:3072
	s_add_u32 s10, s10, 0x6000
	s_addc_u32 s11, s11, 0
	s_add_u32 s12, s12, 0x6000
	s_addc_u32 s13, s13, 0
	global_load_dwordx4 v[16:19], v56, s[0:1] nt
	global_load_dwordx4 v[20:23], v56, s[0:1] offset:1024 nt
	global_load_dwordx4 v[24:27], v56, s[0:1] offset:2048 nt
	global_load_dwordx4 v[28:31], v56, s[0:1] offset:3072 nt
	s_add_u32 s0, s0, 0x800000
	s_addc_u32 s1, s1, 0
	global_load_dwordx4 v[32:35], v56, s[0:1] nt
	global_load_dwordx4 v[36:39], v56, s[0:1] offset:1024 nt
	global_load_dwordx4 v[40:43], v56, s[0:1] offset:2048 nt
	global_load_dwordx4 v[44:47], v56, s[0:1] offset:3072 nt
	s_add_u32 s0, s0, 0x800000
	s_addc_u32 s1, s1, 0
	global_load_dwordx4 v[68:71], v56, s[0:1] nt
	global_load_dwordx4 v[72:75], v56, s[0:1] offset:1024 nt
	global_load_dwordx4 v[76:79], v56, s[0:1] offset:2048 nt
	global_load_dwordx4 v[80:83], v56, s[0:1] offset:3072 nt
	s_add_u32 s0, s0, 0x800000
	s_addc_u32 s1, s1, 0
	global_load_dwordx4 v[132:135], v56, s[10:11]
	global_load_dwordx4 v[136:139], v56, s[10:11] offset:1024
	global_load_dwordx4 v[140:143], v56, s[10:11] offset:2048
	global_load_dwordx4 v[144:147], v56, s[10:11] offset:3072
	global_load_dwordx4 v[116:119], v56, s[12:13]
	global_load_dwordx4 v[120:123], v56, s[12:13] offset:1024
	global_load_dwordx4 v[124:127], v56, s[12:13] offset:2048
	global_load_dwordx4 v[128:131], v56, s[12:13] offset:3072
	s_add_u32 s10, s10, 0x6000
	s_addc_u32 s11, s11, 0
	s_add_u32 s12, s12, 0x6000
	s_addc_u32 s13, s13, 0
	s_waitcnt vmcnt(16)
	v_pk_mul_f32 v[58:59], v[16:17], v[16:17]
	v_pk_fma_f32 v[58:59], v[18:19], v[18:19], v[58:59]
	v_pk_fma_f32 v[58:59], v[20:21], v[20:21], v[58:59]
	v_pk_fma_f32 v[58:59], v[22:23], v[22:23], v[58:59]
	v_pk_fma_f32 v[58:59], v[24:25], v[24:25], v[58:59]
	v_pk_fma_f32 v[58:59], v[26:27], v[26:27], v[58:59]
	v_pk_fma_f32 v[58:59], v[28:29], v[28:29], v[58:59]
	v_pk_fma_f32 v[58:59], v[30:31], v[30:31], v[58:59]
	v_add_f32_e32 v60, v58, v59
	s_nop 1
	v_add_f32_dpp v61, v60, v60 quad_perm:[1,0,3,2] row_mask:0xf bank_mask:0xf
	s_nop 1
	v_add_f32_dpp v60, v61, v61 quad_perm:[2,3,0,1] row_mask:0xf bank_mask:0xf
	s_nop 1
	v_add_f32_dpp v61, v60, v60 row_half_mirror row_mask:0xf bank_mask:0xf
	s_nop 1
	v_add_f32_dpp v60, v61, v61 row_mirror row_mask:0xf bank_mask:0xf
	v_mov_b32_e32 v61, v60
	s_nop 1
	v_add_f32_dpp v61, v60, v60 row_bcast:15 row_mask:0xa bank_mask:0xf
	s_nop 1
	v_mov_b32_e32 v60, v61
	s_nop 1
	v_add_f32_dpp v60, v61, v61 row_bcast:31 row_mask:0xc bank_mask:0xf
	s_nop 1
	v_readlane_b32 s16, v60, 63
	s_nop 1
	v_mov_b32_e32 v148, s16
	v_fmamk_f32 v148, v148, 0x3a800000, v66
	v_rsq_f32_e32 v148, v148
	s_nop 0
	s_waitcnt vmcnt(20)
	v_pk_mul_f32 v[16:17], v[16:17], v[148:149] op_sel_hi:[1,0]
	v_pk_mul_f32 v[18:19], v[18:19], v[148:149] op_sel_hi:[1,0]
	v_pk_add_f32 v[84:85], v[84:85], 1.0 op_sel_hi:[1,0]
	v_pk_add_f32 v[86:87], v[86:87], 1.0 op_sel_hi:[1,0]
	v_pk_mul_f32 v[16:17], v[0:1], v[16:17]
	v_pk_mul_f32 v[18:19], v[2:3], v[18:19]
	v_pk_fma_f32 v[16:17], v[16:17], v[84:85], v[100:101]
	v_pk_fma_f32 v[18:19], v[18:19], v[86:87], v[102:103]
	v_cvt_pk_bf16_f32 v16, v16, v17
	v_cvt_pk_bf16_f32 v17, v18, v19
	global_store_dwordx2 v48, v[16:17], s[14:15]
	v_pk_mul_f32 v[20:21], v[20:21], v[148:149] op_sel_hi:[1,0]
	v_pk_mul_f32 v[22:23], v[22:23], v[148:149] op_sel_hi:[1,0]
	v_pk_add_f32 v[88:89], v[88:89], 1.0 op_sel_hi:[1,0]
	v_pk_add_f32 v[90:91], v[90:91], 1.0 op_sel_hi:[1,0]
	v_pk_mul_f32 v[20:21], v[4:5], v[20:21]
	v_pk_mul_f32 v[22:23], v[6:7], v[22:23]
	v_pk_fma_f32 v[20:21], v[20:21], v[88:89], v[104:105]
	v_pk_fma_f32 v[22:23], v[22:23], v[90:91], v[106:107]
	v_cvt_pk_bf16_f32 v20, v20, v21
	v_cvt_pk_bf16_f32 v21, v22, v23
	global_store_dwordx2 v48, v[20:21], s[14:15] offset:512
	v_pk_mul_f32 v[24:25], v[24:25], v[148:149] op_sel_hi:[1,0]
	v_pk_mul_f32 v[26:27], v[26:27], v[148:149] op_sel_hi:[1,0]
	v_pk_add_f32 v[92:93], v[92:93], 1.0 op_sel_hi:[1,0]
	v_pk_add_f32 v[94:95], v[94:95], 1.0 op_sel_hi:[1,0]
	v_pk_mul_f32 v[24:25], v[8:9], v[24:25]
	v_pk_mul_f32 v[26:27], v[10:11], v[26:27]
	v_pk_fma_f32 v[24:25], v[24:25], v[92:93], v[108:109]
	v_pk_fma_f32 v[26:27], v[26:27], v[94:95], v[110:111]
	v_cvt_pk_bf16_f32 v24, v24, v25
	v_cvt_pk_bf16_f32 v25, v26, v27
	global_store_dwordx2 v48, v[24:25], s[14:15] offset:1024
	v_pk_mul_f32 v[28:29], v[28:29], v[148:149] op_sel_hi:[1,0]
	v_pk_mul_f32 v[30:31], v[30:31], v[148:149] op_sel_hi:[1,0]
	v_pk_add_f32 v[96:97], v[96:97], 1.0 op_sel_hi:[1,0]
	v_pk_add_f32 v[98:99], v[98:99], 1.0 op_sel_hi:[1,0]
	v_pk_mul_f32 v[28:29], v[12:13], v[28:29]
	v_pk_mul_f32 v[30:31], v[14:15], v[30:31]
	v_pk_fma_f32 v[28:29], v[28:29], v[96:97], v[112:113]
	v_pk_fma_f32 v[30:31], v[30:31], v[98:99], v[114:115]
	v_cvt_pk_bf16_f32 v28, v28, v29
	v_cvt_pk_bf16_f32 v29, v30, v31
	global_store_dwordx2 v48, v[28:29], s[14:15] offset:1536
	s_add_u32 s14, s14, 0x400000
	s_addc_u32 s15, s15, 0
	global_load_dwordx4 v[16:19], v56, s[0:1] nt
	global_load_dwordx4 v[20:23], v56, s[0:1] offset:1024 nt
	global_load_dwordx4 v[24:27], v56, s[0:1] offset:2048 nt
	global_load_dwordx4 v[28:31], v56, s[0:1] offset:3072 nt
	s_add_u32 s0, s0, 0x800000
	s_addc_u32 s1, s1, 0
	global_load_dwordx4 v[100:103], v56, s[10:11]
	global_load_dwordx4 v[104:107], v56, s[10:11] offset:1024
	global_load_dwordx4 v[108:111], v56, s[10:11] offset:2048
	global_load_dwordx4 v[112:115], v56, s[10:11] offset:3072
	global_load_dwordx4 v[84:87], v56, s[12:13]
	global_load_dwordx4 v[88:91], v56, s[12:13] offset:1024
	global_load_dwordx4 v[92:95], v56, s[12:13] offset:2048
	global_load_dwordx4 v[96:99], v56, s[12:13] offset:3072
	s_add_u32 s10, s10, 0x6000
	s_addc_u32 s11, s11, 0
	s_add_u32 s12, s12, 0x6000
	s_addc_u32 s13, s13, 0
	s_waitcnt vmcnt(28)
	v_pk_mul_f32 v[58:59], v[32:33], v[32:33]
	v_pk_fma_f32 v[58:59], v[34:35], v[34:35], v[58:59]
	v_pk_fma_f32 v[58:59], v[36:37], v[36:37], v[58:59]
	v_pk_fma_f32 v[58:59], v[38:39], v[38:39], v[58:59]
	v_pk_fma_f32 v[58:59], v[40:41], v[40:41], v[58:59]
	v_pk_fma_f32 v[58:59], v[42:43], v[42:43], v[58:59]
	v_pk_fma_f32 v[58:59], v[44:45], v[44:45], v[58:59]
	v_pk_fma_f32 v[58:59], v[46:47], v[46:47], v[58:59]
	v_add_f32_e32 v60, v58, v59
	s_nop 1
	v_add_f32_dpp v61, v60, v60 quad_perm:[1,0,3,2] row_mask:0xf bank_mask:0xf
	s_nop 1
	v_add_f32_dpp v60, v61, v61 quad_perm:[2,3,0,1] row_mask:0xf bank_mask:0xf
	s_nop 1
	v_add_f32_dpp v61, v60, v60 row_half_mirror row_mask:0xf bank_mask:0xf
	s_nop 1
	v_add_f32_dpp v60, v61, v61 row_mirror row_mask:0xf bank_mask:0xf
	v_mov_b32_e32 v61, v60
	s_nop 1
	v_add_f32_dpp v61, v60, v60 row_bcast:15 row_mask:0xa bank_mask:0xf
	s_nop 1
	v_mov_b32_e32 v60, v61
	s_nop 1
	v_add_f32_dpp v60, v61, v61 row_bcast:31 row_mask:0xc bank_mask:0xf
	s_nop 1
	v_readlane_b32 s16, v60, 63
	s_nop 1
	v_mov_b32_e32 v148, s16
	v_fmamk_f32 v148, v148, 0x3a800000, v66
	v_rsq_f32_e32 v148, v148
	s_nop 0
	s_waitcnt vmcnt(16)
	v_pk_mul_f32 v[32:33], v[32:33], v[148:149] op_sel_hi:[1,0]
	v_pk_mul_f32 v[34:35], v[34:35], v[148:149] op_sel_hi:[1,0]
	v_pk_add_f32 v[116:117], v[116:117], 1.0 op_sel_hi:[1,0]
	v_pk_add_f32 v[118:119], v[118:119], 1.0 op_sel_hi:[1,0]
	v_pk_mul_f32 v[32:33], v[0:1], v[32:33]
	v_pk_mul_f32 v[34:35], v[2:3], v[34:35]
	v_pk_fma_f32 v[32:33], v[32:33], v[116:117], v[132:133]
	v_pk_fma_f32 v[34:35], v[34:35], v[118:119], v[134:135]
	v_cvt_pk_bf16_f32 v32, v32, v33
	v_cvt_pk_bf16_f32 v33, v34, v35
	global_store_dwordx2 v48, v[32:33], s[14:15]
	v_pk_mul_f32 v[36:37], v[36:37], v[148:149] op_sel_hi:[1,0]
	v_pk_mul_f32 v[38:39], v[38:39], v[148:149] op_sel_hi:[1,0]
	v_pk_add_f32 v[120:121], v[120:121], 1.0 op_sel_hi:[1,0]
	v_pk_add_f32 v[122:123], v[122:123], 1.0 op_sel_hi:[1,0]
	v_pk_mul_f32 v[36:37], v[4:5], v[36:37]
	v_pk_mul_f32 v[38:39], v[6:7], v[38:39]
	v_pk_fma_f32 v[36:37], v[36:37], v[120:121], v[136:137]
	v_pk_fma_f32 v[38:39], v[38:39], v[122:123], v[138:139]
	v_cvt_pk_bf16_f32 v36, v36, v37
	v_cvt_pk_bf16_f32 v37, v38, v39
	global_store_dwordx2 v48, v[36:37], s[14:15] offset:512
	v_pk_mul_f32 v[40:41], v[40:41], v[148:149] op_sel_hi:[1,0]
	v_pk_mul_f32 v[42:43], v[42:43], v[148:149] op_sel_hi:[1,0]
	v_pk_add_f32 v[124:125], v[124:125], 1.0 op_sel_hi:[1,0]
	v_pk_add_f32 v[126:127], v[126:127], 1.0 op_sel_hi:[1,0]
	v_pk_mul_f32 v[40:41], v[8:9], v[40:41]
	v_pk_mul_f32 v[42:43], v[10:11], v[42:43]
	v_pk_fma_f32 v[40:41], v[40:41], v[124:125], v[140:141]
	v_pk_fma_f32 v[42:43], v[42:43], v[126:127], v[142:143]
	v_cvt_pk_bf16_f32 v40, v40, v41
	v_cvt_pk_bf16_f32 v41, v42, v43
	global_store_dwordx2 v48, v[40:41], s[14:15] offset:1024
	v_pk_mul_f32 v[44:45], v[44:45], v[148:149] op_sel_hi:[1,0]
	v_pk_mul_f32 v[46:47], v[46:47], v[148:149] op_sel_hi:[1,0]
	v_pk_add_f32 v[128:129], v[128:129], 1.0 op_sel_hi:[1,0]
	v_pk_add_f32 v[130:131], v[130:131], 1.0 op_sel_hi:[1,0]
	v_pk_mul_f32 v[44:45], v[12:13], v[44:45]
	v_pk_mul_f32 v[46:47], v[14:15], v[46:47]
	v_pk_fma_f32 v[44:45], v[44:45], v[128:129], v[144:145]
	v_pk_fma_f32 v[46:47], v[46:47], v[130:131], v[146:147]
	v_cvt_pk_bf16_f32 v44, v44, v45
	v_cvt_pk_bf16_f32 v45, v46, v47
	global_store_dwordx2 v48, v[44:45], s[14:15] offset:1536
	s_add_u32 s14, s14, 0x400000
	s_addc_u32 s15, s15, 0
	global_load_dwordx4 v[32:35], v56, s[0:1] nt
	global_load_dwordx4 v[36:39], v56, s[0:1] offset:1024 nt
	global_load_dwordx4 v[40:43], v56, s[0:1] offset:2048 nt
	global_load_dwordx4 v[44:47], v56, s[0:1] offset:3072 nt
	s_add_u32 s0, s0, 0x800000
	s_addc_u32 s1, s1, 0
	global_load_dwordx4 v[132:135], v56, s[10:11]
	global_load_dwordx4 v[136:139], v56, s[10:11] offset:1024
	global_load_dwordx4 v[140:143], v56, s[10:11] offset:2048
	global_load_dwordx4 v[144:147], v56, s[10:11] offset:3072
	global_load_dwordx4 v[116:119], v56, s[12:13]
	global_load_dwordx4 v[120:123], v56, s[12:13] offset:1024
	global_load_dwordx4 v[124:127], v56, s[12:13] offset:2048
	global_load_dwordx4 v[128:131], v56, s[12:13] offset:3072
	s_add_u32 s10, s10, 0x6000
	s_addc_u32 s11, s11, 0
	s_add_u32 s12, s12, 0x6000
	s_addc_u32 s13, s13, 0
	s_waitcnt vmcnt(40)
	v_pk_mul_f32 v[58:59], v[68:69], v[68:69]
	v_pk_fma_f32 v[58:59], v[70:71], v[70:71], v[58:59]
	v_pk_fma_f32 v[58:59], v[72:73], v[72:73], v[58:59]
	v_pk_fma_f32 v[58:59], v[74:75], v[74:75], v[58:59]
	v_pk_fma_f32 v[58:59], v[76:77], v[76:77], v[58:59]
	v_pk_fma_f32 v[58:59], v[78:79], v[78:79], v[58:59]
	v_pk_fma_f32 v[58:59], v[80:81], v[80:81], v[58:59]
	v_pk_fma_f32 v[58:59], v[82:83], v[82:83], v[58:59]
	v_add_f32_e32 v60, v58, v59
	s_nop 1
	v_add_f32_dpp v61, v60, v60 quad_perm:[1,0,3,2] row_mask:0xf bank_mask:0xf
	s_nop 1
	v_add_f32_dpp v60, v61, v61 quad_perm:[2,3,0,1] row_mask:0xf bank_mask:0xf
	s_nop 1
	v_add_f32_dpp v61, v60, v60 row_half_mirror row_mask:0xf bank_mask:0xf
	s_nop 1
	v_add_f32_dpp v60, v61, v61 row_mirror row_mask:0xf bank_mask:0xf
	v_mov_b32_e32 v61, v60
	s_nop 1
	v_add_f32_dpp v61, v60, v60 row_bcast:15 row_mask:0xa bank_mask:0xf
	s_nop 1
	v_mov_b32_e32 v60, v61
	s_nop 1
	v_add_f32_dpp v60, v61, v61 row_bcast:31 row_mask:0xc bank_mask:0xf
	s_nop 1
	v_readlane_b32 s16, v60, 63
	s_nop 1
	v_mov_b32_e32 v148, s16
	v_fmamk_f32 v148, v148, 0x3a800000, v66
	v_rsq_f32_e32 v148, v148
	s_nop 0
	s_waitcnt vmcnt(16)
	v_pk_mul_f32 v[68:69], v[68:69], v[148:149] op_sel_hi:[1,0]
	v_pk_mul_f32 v[70:71], v[70:71], v[148:149] op_sel_hi:[1,0]
	v_pk_add_f32 v[84:85], v[84:85], 1.0 op_sel_hi:[1,0]
	v_pk_add_f32 v[86:87], v[86:87], 1.0 op_sel_hi:[1,0]
	v_pk_mul_f32 v[68:69], v[0:1], v[68:69]
	v_pk_mul_f32 v[70:71], v[2:3], v[70:71]
	v_pk_fma_f32 v[68:69], v[68:69], v[84:85], v[100:101]
	v_pk_fma_f32 v[70:71], v[70:71], v[86:87], v[102:103]
	v_cvt_pk_bf16_f32 v68, v68, v69
	v_cvt_pk_bf16_f32 v69, v70, v71
	global_store_dwordx2 v48, v[68:69], s[14:15]
	v_pk_mul_f32 v[72:73], v[72:73], v[148:149] op_sel_hi:[1,0]
	v_pk_mul_f32 v[74:75], v[74:75], v[148:149] op_sel_hi:[1,0]
	v_pk_add_f32 v[88:89], v[88:89], 1.0 op_sel_hi:[1,0]
	v_pk_add_f32 v[90:91], v[90:91], 1.0 op_sel_hi:[1,0]
	v_pk_mul_f32 v[72:73], v[4:5], v[72:73]
	v_pk_mul_f32 v[74:75], v[6:7], v[74:75]
	v_pk_fma_f32 v[72:73], v[72:73], v[88:89], v[104:105]
	v_pk_fma_f32 v[74:75], v[74:75], v[90:91], v[106:107]
	v_cvt_pk_bf16_f32 v72, v72, v73
	v_cvt_pk_bf16_f32 v73, v74, v75
	global_store_dwordx2 v48, v[72:73], s[14:15] offset:512
	v_pk_mul_f32 v[76:77], v[76:77], v[148:149] op_sel_hi:[1,0]
	v_pk_mul_f32 v[78:79], v[78:79], v[148:149] op_sel_hi:[1,0]
	v_pk_add_f32 v[92:93], v[92:93], 1.0 op_sel_hi:[1,0]
	v_pk_add_f32 v[94:95], v[94:95], 1.0 op_sel_hi:[1,0]
	v_pk_mul_f32 v[76:77], v[8:9], v[76:77]
	v_pk_mul_f32 v[78:79], v[10:11], v[78:79]
	v_pk_fma_f32 v[76:77], v[76:77], v[92:93], v[108:109]
	v_pk_fma_f32 v[78:79], v[78:79], v[94:95], v[110:111]
	v_cvt_pk_bf16_f32 v76, v76, v77
	v_cvt_pk_bf16_f32 v77, v78, v79
	global_store_dwordx2 v48, v[76:77], s[14:15] offset:1024
	v_pk_mul_f32 v[80:81], v[80:81], v[148:149] op_sel_hi:[1,0]
	v_pk_mul_f32 v[82:83], v[82:83], v[148:149] op_sel_hi:[1,0]
	v_pk_add_f32 v[96:97], v[96:97], 1.0 op_sel_hi:[1,0]
	v_pk_add_f32 v[98:99], v[98:99], 1.0 op_sel_hi:[1,0]
	v_pk_mul_f32 v[80:81], v[12:13], v[80:81]
	v_pk_mul_f32 v[82:83], v[14:15], v[82:83]
	v_pk_fma_f32 v[80:81], v[80:81], v[96:97], v[112:113]
	v_pk_fma_f32 v[82:83], v[82:83], v[98:99], v[114:115]
	v_cvt_pk_bf16_f32 v80, v80, v81
	v_cvt_pk_bf16_f32 v81, v82, v83
	global_store_dwordx2 v48, v[80:81], s[14:15] offset:1536
	s_add_u32 s14, s14, 0x400000
	s_addc_u32 s15, s15, 0
	global_load_dwordx4 v[68:71], v56, s[0:1] nt
	global_load_dwordx4 v[72:75], v56, s[0:1] offset:1024 nt
	global_load_dwordx4 v[76:79], v56, s[0:1] offset:2048 nt
	global_load_dwordx4 v[80:83], v56, s[0:1] offset:3072 nt
	s_add_u32 s0, s0, 0x800000
	s_addc_u32 s1, s1, 0
	global_load_dwordx4 v[100:103], v56, s[10:11]
	global_load_dwordx4 v[104:107], v56, s[10:11] offset:1024
	global_load_dwordx4 v[108:111], v56, s[10:11] offset:2048
	global_load_dwordx4 v[112:115], v56, s[10:11] offset:3072
	global_load_dwordx4 v[84:87], v56, s[12:13]
	global_load_dwordx4 v[88:91], v56, s[12:13] offset:1024
	global_load_dwordx4 v[92:95], v56, s[12:13] offset:2048
	global_load_dwordx4 v[96:99], v56, s[12:13] offset:3072
	s_add_u32 s10, s10, 0x6000
	s_addc_u32 s11, s11, 0
	s_add_u32 s12, s12, 0x6000
	s_addc_u32 s13, s13, 0
	s_waitcnt vmcnt(40)
	v_pk_mul_f32 v[58:59], v[16:17], v[16:17]
	v_pk_fma_f32 v[58:59], v[18:19], v[18:19], v[58:59]
	v_pk_fma_f32 v[58:59], v[20:21], v[20:21], v[58:59]
	v_pk_fma_f32 v[58:59], v[22:23], v[22:23], v[58:59]
	v_pk_fma_f32 v[58:59], v[24:25], v[24:25], v[58:59]
	v_pk_fma_f32 v[58:59], v[26:27], v[26:27], v[58:59]
	v_pk_fma_f32 v[58:59], v[28:29], v[28:29], v[58:59]
	v_pk_fma_f32 v[58:59], v[30:31], v[30:31], v[58:59]
	v_add_f32_e32 v60, v58, v59
	s_nop 1
	v_add_f32_dpp v61, v60, v60 quad_perm:[1,0,3,2] row_mask:0xf bank_mask:0xf
	s_nop 1
	v_add_f32_dpp v60, v61, v61 quad_perm:[2,3,0,1] row_mask:0xf bank_mask:0xf
	s_nop 1
	v_add_f32_dpp v61, v60, v60 row_half_mirror row_mask:0xf bank_mask:0xf
	s_nop 1
	v_add_f32_dpp v60, v61, v61 row_mirror row_mask:0xf bank_mask:0xf
	v_mov_b32_e32 v61, v60
	s_nop 1
	v_add_f32_dpp v61, v60, v60 row_bcast:15 row_mask:0xa bank_mask:0xf
	s_nop 1
	v_mov_b32_e32 v60, v61
	s_nop 1
	v_add_f32_dpp v60, v61, v61 row_bcast:31 row_mask:0xc bank_mask:0xf
	s_nop 1
	v_readlane_b32 s16, v60, 63
	s_nop 1
	v_mov_b32_e32 v148, s16
	v_fmamk_f32 v148, v148, 0x3a800000, v66
	v_rsq_f32_e32 v148, v148
	s_nop 0
	s_waitcnt vmcnt(16)
	v_pk_mul_f32 v[16:17], v[16:17], v[148:149] op_sel_hi:[1,0]
	v_pk_mul_f32 v[18:19], v[18:19], v[148:149] op_sel_hi:[1,0]
	v_pk_add_f32 v[116:117], v[116:117], 1.0 op_sel_hi:[1,0]
	v_pk_add_f32 v[118:119], v[118:119], 1.0 op_sel_hi:[1,0]
	v_pk_mul_f32 v[16:17], v[0:1], v[16:17]
	v_pk_mul_f32 v[18:19], v[2:3], v[18:19]
	v_pk_fma_f32 v[16:17], v[16:17], v[116:117], v[132:133]
	v_pk_fma_f32 v[18:19], v[18:19], v[118:119], v[134:135]
	v_cvt_pk_bf16_f32 v16, v16, v17
	v_cvt_pk_bf16_f32 v17, v18, v19
	global_store_dwordx2 v48, v[16:17], s[14:15]
	v_pk_mul_f32 v[20:21], v[20:21], v[148:149] op_sel_hi:[1,0]
	v_pk_mul_f32 v[22:23], v[22:23], v[148:149] op_sel_hi:[1,0]
	v_pk_add_f32 v[120:121], v[120:121], 1.0 op_sel_hi:[1,0]
	v_pk_add_f32 v[122:123], v[122:123], 1.0 op_sel_hi:[1,0]
	v_pk_mul_f32 v[20:21], v[4:5], v[20:21]
	v_pk_mul_f32 v[22:23], v[6:7], v[22:23]
	v_pk_fma_f32 v[20:21], v[20:21], v[120:121], v[136:137]
	v_pk_fma_f32 v[22:23], v[22:23], v[122:123], v[138:139]
	v_cvt_pk_bf16_f32 v20, v20, v21
	v_cvt_pk_bf16_f32 v21, v22, v23
	global_store_dwordx2 v48, v[20:21], s[14:15] offset:512
	v_pk_mul_f32 v[24:25], v[24:25], v[148:149] op_sel_hi:[1,0]
	v_pk_mul_f32 v[26:27], v[26:27], v[148:149] op_sel_hi:[1,0]
	v_pk_add_f32 v[124:125], v[124:125], 1.0 op_sel_hi:[1,0]
	v_pk_add_f32 v[126:127], v[126:127], 1.0 op_sel_hi:[1,0]
	v_pk_mul_f32 v[24:25], v[8:9], v[24:25]
	v_pk_mul_f32 v[26:27], v[10:11], v[26:27]
	v_pk_fma_f32 v[24:25], v[24:25], v[124:125], v[140:141]
	v_pk_fma_f32 v[26:27], v[26:27], v[126:127], v[142:143]
	v_cvt_pk_bf16_f32 v24, v24, v25
	v_cvt_pk_bf16_f32 v25, v26, v27
	global_store_dwordx2 v48, v[24:25], s[14:15] offset:1024
	v_pk_mul_f32 v[28:29], v[28:29], v[148:149] op_sel_hi:[1,0]
	v_pk_mul_f32 v[30:31], v[30:31], v[148:149] op_sel_hi:[1,0]
	v_pk_add_f32 v[128:129], v[128:129], 1.0 op_sel_hi:[1,0]
	v_pk_add_f32 v[130:131], v[130:131], 1.0 op_sel_hi:[1,0]
	v_pk_mul_f32 v[28:29], v[12:13], v[28:29]
	v_pk_mul_f32 v[30:31], v[14:15], v[30:31]
	v_pk_fma_f32 v[28:29], v[28:29], v[128:129], v[144:145]
	v_pk_fma_f32 v[30:31], v[30:31], v[130:131], v[146:147]
	v_cvt_pk_bf16_f32 v28, v28, v29
	v_cvt_pk_bf16_f32 v29, v30, v31
	global_store_dwordx2 v48, v[28:29], s[14:15] offset:1536
	s_add_u32 s14, s14, 0x400000
	s_addc_u32 s15, s15, 0
	global_load_dwordx4 v[16:19], v56, s[0:1] nt
	global_load_dwordx4 v[20:23], v56, s[0:1] offset:1024 nt
	global_load_dwordx4 v[24:27], v56, s[0:1] offset:2048 nt
	global_load_dwordx4 v[28:31], v56, s[0:1] offset:3072 nt
	s_add_u32 s0, s0, 0x800000
	s_addc_u32 s1, s1, 0
	global_load_dwordx4 v[132:135], v56, s[10:11]
	global_load_dwordx4 v[136:139], v56, s[10:11] offset:1024
	global_load_dwordx4 v[140:143], v56, s[10:11] offset:2048
	global_load_dwordx4 v[144:147], v56, s[10:11] offset:3072
	global_load_dwordx4 v[116:119], v56, s[12:13]
	global_load_dwordx4 v[120:123], v56, s[12:13] offset:1024
	global_load_dwordx4 v[124:127], v56, s[12:13] offset:2048
	global_load_dwordx4 v[128:131], v56, s[12:13] offset:3072
	s_add_u32 s10, s10, 0x6000
	s_addc_u32 s11, s11, 0
	s_add_u32 s12, s12, 0x6000
	s_addc_u32 s13, s13, 0
	s_waitcnt vmcnt(40)
	v_pk_mul_f32 v[58:59], v[32:33], v[32:33]
	v_pk_fma_f32 v[58:59], v[34:35], v[34:35], v[58:59]
	v_pk_fma_f32 v[58:59], v[36:37], v[36:37], v[58:59]
	v_pk_fma_f32 v[58:59], v[38:39], v[38:39], v[58:59]
	v_pk_fma_f32 v[58:59], v[40:41], v[40:41], v[58:59]
	v_pk_fma_f32 v[58:59], v[42:43], v[42:43], v[58:59]
	v_pk_fma_f32 v[58:59], v[44:45], v[44:45], v[58:59]
	v_pk_fma_f32 v[58:59], v[46:47], v[46:47], v[58:59]
	v_add_f32_e32 v60, v58, v59
	s_nop 1
	v_add_f32_dpp v61, v60, v60 quad_perm:[1,0,3,2] row_mask:0xf bank_mask:0xf
	s_nop 1
	v_add_f32_dpp v60, v61, v61 quad_perm:[2,3,0,1] row_mask:0xf bank_mask:0xf
	s_nop 1
	v_add_f32_dpp v61, v60, v60 row_half_mirror row_mask:0xf bank_mask:0xf
	s_nop 1
	v_add_f32_dpp v60, v61, v61 row_mirror row_mask:0xf bank_mask:0xf
	v_mov_b32_e32 v61, v60
	s_nop 1
	v_add_f32_dpp v61, v60, v60 row_bcast:15 row_mask:0xa bank_mask:0xf
	s_nop 1
	v_mov_b32_e32 v60, v61
	s_nop 1
	v_add_f32_dpp v60, v61, v61 row_bcast:31 row_mask:0xc bank_mask:0xf
	s_nop 1
	v_readlane_b32 s16, v60, 63
	s_nop 1
	v_mov_b32_e32 v148, s16
	v_fmamk_f32 v148, v148, 0x3a800000, v66
	v_rsq_f32_e32 v148, v148
	s_nop 0
	s_waitcnt vmcnt(16)
	v_pk_mul_f32 v[32:33], v[32:33], v[148:149] op_sel_hi:[1,0]
	v_pk_mul_f32 v[34:35], v[34:35], v[148:149] op_sel_hi:[1,0]
	v_pk_add_f32 v[84:85], v[84:85], 1.0 op_sel_hi:[1,0]
	v_pk_add_f32 v[86:87], v[86:87], 1.0 op_sel_hi:[1,0]
	v_pk_mul_f32 v[32:33], v[0:1], v[32:33]
	v_pk_mul_f32 v[34:35], v[2:3], v[34:35]
	v_pk_fma_f32 v[32:33], v[32:33], v[84:85], v[100:101]
	v_pk_fma_f32 v[34:35], v[34:35], v[86:87], v[102:103]
	v_cvt_pk_bf16_f32 v32, v32, v33
	v_cvt_pk_bf16_f32 v33, v34, v35
	global_store_dwordx2 v48, v[32:33], s[14:15]
	v_pk_mul_f32 v[36:37], v[36:37], v[148:149] op_sel_hi:[1,0]
	v_pk_mul_f32 v[38:39], v[38:39], v[148:149] op_sel_hi:[1,0]
	v_pk_add_f32 v[88:89], v[88:89], 1.0 op_sel_hi:[1,0]
	v_pk_add_f32 v[90:91], v[90:91], 1.0 op_sel_hi:[1,0]
	v_pk_mul_f32 v[36:37], v[4:5], v[36:37]
	v_pk_mul_f32 v[38:39], v[6:7], v[38:39]
	v_pk_fma_f32 v[36:37], v[36:37], v[88:89], v[104:105]
	v_pk_fma_f32 v[38:39], v[38:39], v[90:91], v[106:107]
	v_cvt_pk_bf16_f32 v36, v36, v37
	v_cvt_pk_bf16_f32 v37, v38, v39
	global_store_dwordx2 v48, v[36:37], s[14:15] offset:512
	v_pk_mul_f32 v[40:41], v[40:41], v[148:149] op_sel_hi:[1,0]
	v_pk_mul_f32 v[42:43], v[42:43], v[148:149] op_sel_hi:[1,0]
	v_pk_add_f32 v[92:93], v[92:93], 1.0 op_sel_hi:[1,0]
	v_pk_add_f32 v[94:95], v[94:95], 1.0 op_sel_hi:[1,0]
	v_pk_mul_f32 v[40:41], v[8:9], v[40:41]
	v_pk_mul_f32 v[42:43], v[10:11], v[42:43]
	v_pk_fma_f32 v[40:41], v[40:41], v[92:93], v[108:109]
	v_pk_fma_f32 v[42:43], v[42:43], v[94:95], v[110:111]
	v_cvt_pk_bf16_f32 v40, v40, v41
	v_cvt_pk_bf16_f32 v41, v42, v43
	global_store_dwordx2 v48, v[40:41], s[14:15] offset:1024
	v_pk_mul_f32 v[44:45], v[44:45], v[148:149] op_sel_hi:[1,0]
	v_pk_mul_f32 v[46:47], v[46:47], v[148:149] op_sel_hi:[1,0]
	v_pk_add_f32 v[96:97], v[96:97], 1.0 op_sel_hi:[1,0]
	v_pk_add_f32 v[98:99], v[98:99], 1.0 op_sel_hi:[1,0]
	v_pk_mul_f32 v[44:45], v[12:13], v[44:45]
	v_pk_mul_f32 v[46:47], v[14:15], v[46:47]
	v_pk_fma_f32 v[44:45], v[44:45], v[96:97], v[112:113]
	v_pk_fma_f32 v[46:47], v[46:47], v[98:99], v[114:115]
	v_cvt_pk_bf16_f32 v44, v44, v45
	v_cvt_pk_bf16_f32 v45, v46, v47
	global_store_dwordx2 v48, v[44:45], s[14:15] offset:1536
	s_add_u32 s14, s14, 0x400000
	s_addc_u32 s15, s15, 0
	global_load_dwordx4 v[32:35], v56, s[0:1] nt
	global_load_dwordx4 v[36:39], v56, s[0:1] offset:1024 nt
	global_load_dwordx4 v[40:43], v56, s[0:1] offset:2048 nt
	global_load_dwordx4 v[44:47], v56, s[0:1] offset:3072 nt
	s_add_u32 s0, s0, 0x800000
	s_addc_u32 s1, s1, 0
	global_load_dwordx4 v[100:103], v56, s[10:11]
	global_load_dwordx4 v[104:107], v56, s[10:11] offset:1024
	global_load_dwordx4 v[108:111], v56, s[10:11] offset:2048
	global_load_dwordx4 v[112:115], v56, s[10:11] offset:3072
	global_load_dwordx4 v[84:87], v56, s[12:13]
	global_load_dwordx4 v[88:91], v56, s[12:13] offset:1024
	global_load_dwordx4 v[92:95], v56, s[12:13] offset:2048
	global_load_dwordx4 v[96:99], v56, s[12:13] offset:3072
	s_add_u32 s10, s10, 0x6000
	s_addc_u32 s11, s11, 0
	s_add_u32 s12, s12, 0x6000
	s_addc_u32 s13, s13, 0
	s_waitcnt vmcnt(40)
	v_pk_mul_f32 v[58:59], v[68:69], v[68:69]
	v_pk_fma_f32 v[58:59], v[70:71], v[70:71], v[58:59]
	v_pk_fma_f32 v[58:59], v[72:73], v[72:73], v[58:59]
	v_pk_fma_f32 v[58:59], v[74:75], v[74:75], v[58:59]
	v_pk_fma_f32 v[58:59], v[76:77], v[76:77], v[58:59]
	v_pk_fma_f32 v[58:59], v[78:79], v[78:79], v[58:59]
	v_pk_fma_f32 v[58:59], v[80:81], v[80:81], v[58:59]
	v_pk_fma_f32 v[58:59], v[82:83], v[82:83], v[58:59]
	v_add_f32_e32 v60, v58, v59
	s_nop 1
	v_add_f32_dpp v61, v60, v60 quad_perm:[1,0,3,2] row_mask:0xf bank_mask:0xf
	s_nop 1
	v_add_f32_dpp v60, v61, v61 quad_perm:[2,3,0,1] row_mask:0xf bank_mask:0xf
	s_nop 1
	v_add_f32_dpp v61, v60, v60 row_half_mirror row_mask:0xf bank_mask:0xf
	s_nop 1
	v_add_f32_dpp v60, v61, v61 row_mirror row_mask:0xf bank_mask:0xf
	v_mov_b32_e32 v61, v60
	s_nop 1
	v_add_f32_dpp v61, v60, v60 row_bcast:15 row_mask:0xa bank_mask:0xf
	s_nop 1
	v_mov_b32_e32 v60, v61
	s_nop 1
	v_add_f32_dpp v60, v61, v61 row_bcast:31 row_mask:0xc bank_mask:0xf
	s_nop 1
	v_readlane_b32 s16, v60, 63
	s_nop 1
	v_mov_b32_e32 v148, s16
	v_fmamk_f32 v148, v148, 0x3a800000, v66
	v_rsq_f32_e32 v148, v148
	s_nop 0
	s_waitcnt vmcnt(16)
	v_pk_mul_f32 v[68:69], v[68:69], v[148:149] op_sel_hi:[1,0]
	v_pk_mul_f32 v[70:71], v[70:71], v[148:149] op_sel_hi:[1,0]
	v_pk_add_f32 v[116:117], v[116:117], 1.0 op_sel_hi:[1,0]
	v_pk_add_f32 v[118:119], v[118:119], 1.0 op_sel_hi:[1,0]
	v_pk_mul_f32 v[68:69], v[0:1], v[68:69]
	v_pk_mul_f32 v[70:71], v[2:3], v[70:71]
	v_pk_fma_f32 v[68:69], v[68:69], v[116:117], v[132:133]
	v_pk_fma_f32 v[70:71], v[70:71], v[118:119], v[134:135]
	v_cvt_pk_bf16_f32 v68, v68, v69
	v_cvt_pk_bf16_f32 v69, v70, v71
	global_store_dwordx2 v48, v[68:69], s[14:15]
	v_pk_mul_f32 v[72:73], v[72:73], v[148:149] op_sel_hi:[1,0]
	v_pk_mul_f32 v[74:75], v[74:75], v[148:149] op_sel_hi:[1,0]
	v_pk_add_f32 v[120:121], v[120:121], 1.0 op_sel_hi:[1,0]
	v_pk_add_f32 v[122:123], v[122:123], 1.0 op_sel_hi:[1,0]
	v_pk_mul_f32 v[72:73], v[4:5], v[72:73]
	v_pk_mul_f32 v[74:75], v[6:7], v[74:75]
	v_pk_fma_f32 v[72:73], v[72:73], v[120:121], v[136:137]
	v_pk_fma_f32 v[74:75], v[74:75], v[122:123], v[138:139]
	v_cvt_pk_bf16_f32 v72, v72, v73
	v_cvt_pk_bf16_f32 v73, v74, v75
	global_store_dwordx2 v48, v[72:73], s[14:15] offset:512
	v_pk_mul_f32 v[76:77], v[76:77], v[148:149] op_sel_hi:[1,0]
	v_pk_mul_f32 v[78:79], v[78:79], v[148:149] op_sel_hi:[1,0]
	v_pk_add_f32 v[124:125], v[124:125], 1.0 op_sel_hi:[1,0]
	v_pk_add_f32 v[126:127], v[126:127], 1.0 op_sel_hi:[1,0]
	v_pk_mul_f32 v[76:77], v[8:9], v[76:77]
	v_pk_mul_f32 v[78:79], v[10:11], v[78:79]
	v_pk_fma_f32 v[76:77], v[76:77], v[124:125], v[140:141]
	v_pk_fma_f32 v[78:79], v[78:79], v[126:127], v[142:143]
	v_cvt_pk_bf16_f32 v76, v76, v77
	v_cvt_pk_bf16_f32 v77, v78, v79
	global_store_dwordx2 v48, v[76:77], s[14:15] offset:1024
	v_pk_mul_f32 v[80:81], v[80:81], v[148:149] op_sel_hi:[1,0]
	v_pk_mul_f32 v[82:83], v[82:83], v[148:149] op_sel_hi:[1,0]
	v_pk_add_f32 v[128:129], v[128:129], 1.0 op_sel_hi:[1,0]
	v_pk_add_f32 v[130:131], v[130:131], 1.0 op_sel_hi:[1,0]
	v_pk_mul_f32 v[80:81], v[12:13], v[80:81]
	v_pk_mul_f32 v[82:83], v[14:15], v[82:83]
	v_pk_fma_f32 v[80:81], v[80:81], v[128:129], v[144:145]
	v_pk_fma_f32 v[82:83], v[82:83], v[130:131], v[146:147]
	v_cvt_pk_bf16_f32 v80, v80, v81
	v_cvt_pk_bf16_f32 v81, v82, v83
	global_store_dwordx2 v48, v[80:81], s[14:15] offset:1536
	s_add_u32 s14, s14, 0x400000
	s_addc_u32 s15, s15, 0
	global_load_dwordx4 v[68:71], v56, s[0:1] nt
	global_load_dwordx4 v[72:75], v56, s[0:1] offset:1024 nt
	global_load_dwordx4 v[76:79], v56, s[0:1] offset:2048 nt
	global_load_dwordx4 v[80:83], v56, s[0:1] offset:3072 nt
	s_add_u32 s0, s0, 0x800000
	s_addc_u32 s1, s1, 0
	global_load_dwordx4 v[132:135], v56, s[10:11]
	global_load_dwordx4 v[136:139], v56, s[10:11] offset:1024
	global_load_dwordx4 v[140:143], v56, s[10:11] offset:2048
	global_load_dwordx4 v[144:147], v56, s[10:11] offset:3072
	global_load_dwordx4 v[116:119], v56, s[12:13]
	global_load_dwordx4 v[120:123], v56, s[12:13] offset:1024
	global_load_dwordx4 v[124:127], v56, s[12:13] offset:2048
	global_load_dwordx4 v[128:131], v56, s[12:13] offset:3072
	s_add_u32 s10, s10, 0x6000
	s_addc_u32 s11, s11, 0
	s_add_u32 s12, s12, 0x6000
	s_addc_u32 s13, s13, 0
	s_waitcnt vmcnt(40)
	v_pk_mul_f32 v[58:59], v[16:17], v[16:17]
	v_pk_fma_f32 v[58:59], v[18:19], v[18:19], v[58:59]
	v_pk_fma_f32 v[58:59], v[20:21], v[20:21], v[58:59]
	v_pk_fma_f32 v[58:59], v[22:23], v[22:23], v[58:59]
	v_pk_fma_f32 v[58:59], v[24:25], v[24:25], v[58:59]
	v_pk_fma_f32 v[58:59], v[26:27], v[26:27], v[58:59]
	v_pk_fma_f32 v[58:59], v[28:29], v[28:29], v[58:59]
	v_pk_fma_f32 v[58:59], v[30:31], v[30:31], v[58:59]
	v_add_f32_e32 v60, v58, v59
	s_nop 1
	v_add_f32_dpp v61, v60, v60 quad_perm:[1,0,3,2] row_mask:0xf bank_mask:0xf
	s_nop 1
	v_add_f32_dpp v60, v61, v61 quad_perm:[2,3,0,1] row_mask:0xf bank_mask:0xf
	s_nop 1
	v_add_f32_dpp v61, v60, v60 row_half_mirror row_mask:0xf bank_mask:0xf
	s_nop 1
	v_add_f32_dpp v60, v61, v61 row_mirror row_mask:0xf bank_mask:0xf
	v_mov_b32_e32 v61, v60
	s_nop 1
	v_add_f32_dpp v61, v60, v60 row_bcast:15 row_mask:0xa bank_mask:0xf
	s_nop 1
	v_mov_b32_e32 v60, v61
	s_nop 1
	v_add_f32_dpp v60, v61, v61 row_bcast:31 row_mask:0xc bank_mask:0xf
	s_nop 1
	v_readlane_b32 s16, v60, 63
	s_nop 1
	v_mov_b32_e32 v148, s16
	v_fmamk_f32 v148, v148, 0x3a800000, v66
	v_rsq_f32_e32 v148, v148
	s_nop 0
	s_waitcnt vmcnt(16)
	v_pk_mul_f32 v[16:17], v[16:17], v[148:149] op_sel_hi:[1,0]
	v_pk_mul_f32 v[18:19], v[18:19], v[148:149] op_sel_hi:[1,0]
	v_pk_add_f32 v[84:85], v[84:85], 1.0 op_sel_hi:[1,0]
	v_pk_add_f32 v[86:87], v[86:87], 1.0 op_sel_hi:[1,0]
	v_pk_mul_f32 v[16:17], v[0:1], v[16:17]
	v_pk_mul_f32 v[18:19], v[2:3], v[18:19]
	v_pk_fma_f32 v[16:17], v[16:17], v[84:85], v[100:101]
	v_pk_fma_f32 v[18:19], v[18:19], v[86:87], v[102:103]
	v_cvt_pk_bf16_f32 v16, v16, v17
	v_cvt_pk_bf16_f32 v17, v18, v19
	global_store_dwordx2 v48, v[16:17], s[14:15]
	v_pk_mul_f32 v[20:21], v[20:21], v[148:149] op_sel_hi:[1,0]
	v_pk_mul_f32 v[22:23], v[22:23], v[148:149] op_sel_hi:[1,0]
	v_pk_add_f32 v[88:89], v[88:89], 1.0 op_sel_hi:[1,0]
	v_pk_add_f32 v[90:91], v[90:91], 1.0 op_sel_hi:[1,0]
	v_pk_mul_f32 v[20:21], v[4:5], v[20:21]
	v_pk_mul_f32 v[22:23], v[6:7], v[22:23]
	v_pk_fma_f32 v[20:21], v[20:21], v[88:89], v[104:105]
	v_pk_fma_f32 v[22:23], v[22:23], v[90:91], v[106:107]
	v_cvt_pk_bf16_f32 v20, v20, v21
	v_cvt_pk_bf16_f32 v21, v22, v23
	global_store_dwordx2 v48, v[20:21], s[14:15] offset:512
	v_pk_mul_f32 v[24:25], v[24:25], v[148:149] op_sel_hi:[1,0]
	v_pk_mul_f32 v[26:27], v[26:27], v[148:149] op_sel_hi:[1,0]
	v_pk_add_f32 v[92:93], v[92:93], 1.0 op_sel_hi:[1,0]
	v_pk_add_f32 v[94:95], v[94:95], 1.0 op_sel_hi:[1,0]
	v_pk_mul_f32 v[24:25], v[8:9], v[24:25]
	v_pk_mul_f32 v[26:27], v[10:11], v[26:27]
	v_pk_fma_f32 v[24:25], v[24:25], v[92:93], v[108:109]
	v_pk_fma_f32 v[26:27], v[26:27], v[94:95], v[110:111]
	v_cvt_pk_bf16_f32 v24, v24, v25
	v_cvt_pk_bf16_f32 v25, v26, v27
	global_store_dwordx2 v48, v[24:25], s[14:15] offset:1024
	v_pk_mul_f32 v[28:29], v[28:29], v[148:149] op_sel_hi:[1,0]
	v_pk_mul_f32 v[30:31], v[30:31], v[148:149] op_sel_hi:[1,0]
	v_pk_add_f32 v[96:97], v[96:97], 1.0 op_sel_hi:[1,0]
	v_pk_add_f32 v[98:99], v[98:99], 1.0 op_sel_hi:[1,0]
	v_pk_mul_f32 v[28:29], v[12:13], v[28:29]
	v_pk_mul_f32 v[30:31], v[14:15], v[30:31]
	v_pk_fma_f32 v[28:29], v[28:29], v[96:97], v[112:113]
	v_pk_fma_f32 v[30:31], v[30:31], v[98:99], v[114:115]
	v_cvt_pk_bf16_f32 v28, v28, v29
	v_cvt_pk_bf16_f32 v29, v30, v31
	global_store_dwordx2 v48, v[28:29], s[14:15] offset:1536
	s_add_u32 s14, s14, 0x400000
	s_addc_u32 s15, s15, 0
	global_load_dwordx4 v[16:19], v56, s[0:1] nt
	global_load_dwordx4 v[20:23], v56, s[0:1] offset:1024 nt
	global_load_dwordx4 v[24:27], v56, s[0:1] offset:2048 nt
	global_load_dwordx4 v[28:31], v56, s[0:1] offset:3072 nt
	s_add_u32 s0, s0, 0x800000
	s_addc_u32 s1, s1, 0
	global_load_dwordx4 v[100:103], v56, s[10:11]
	global_load_dwordx4 v[104:107], v56, s[10:11] offset:1024
	global_load_dwordx4 v[108:111], v56, s[10:11] offset:2048
	global_load_dwordx4 v[112:115], v56, s[10:11] offset:3072
	global_load_dwordx4 v[84:87], v56, s[12:13]
	global_load_dwordx4 v[88:91], v56, s[12:13] offset:1024
	global_load_dwordx4 v[92:95], v56, s[12:13] offset:2048
	global_load_dwordx4 v[96:99], v56, s[12:13] offset:3072
	s_add_u32 s10, s10, 0x6000
	s_addc_u32 s11, s11, 0
	s_add_u32 s12, s12, 0x6000
	s_addc_u32 s13, s13, 0
	s_waitcnt vmcnt(40)
	v_pk_mul_f32 v[58:59], v[32:33], v[32:33]
	v_pk_fma_f32 v[58:59], v[34:35], v[34:35], v[58:59]
	v_pk_fma_f32 v[58:59], v[36:37], v[36:37], v[58:59]
	v_pk_fma_f32 v[58:59], v[38:39], v[38:39], v[58:59]
	v_pk_fma_f32 v[58:59], v[40:41], v[40:41], v[58:59]
	v_pk_fma_f32 v[58:59], v[42:43], v[42:43], v[58:59]
	v_pk_fma_f32 v[58:59], v[44:45], v[44:45], v[58:59]
	v_pk_fma_f32 v[58:59], v[46:47], v[46:47], v[58:59]
	v_add_f32_e32 v60, v58, v59
	s_nop 1
	v_add_f32_dpp v61, v60, v60 quad_perm:[1,0,3,2] row_mask:0xf bank_mask:0xf
	s_nop 1
	v_add_f32_dpp v60, v61, v61 quad_perm:[2,3,0,1] row_mask:0xf bank_mask:0xf
	s_nop 1
	v_add_f32_dpp v61, v60, v60 row_half_mirror row_mask:0xf bank_mask:0xf
	s_nop 1
	v_add_f32_dpp v60, v61, v61 row_mirror row_mask:0xf bank_mask:0xf
	v_mov_b32_e32 v61, v60
	s_nop 1
	v_add_f32_dpp v61, v60, v60 row_bcast:15 row_mask:0xa bank_mask:0xf
	s_nop 1
	v_mov_b32_e32 v60, v61
	s_nop 1
	v_add_f32_dpp v60, v61, v61 row_bcast:31 row_mask:0xc bank_mask:0xf
	s_nop 1
	v_readlane_b32 s16, v60, 63
	s_nop 1
	v_mov_b32_e32 v148, s16
	v_fmamk_f32 v148, v148, 0x3a800000, v66
	v_rsq_f32_e32 v148, v148
	s_nop 0
	s_waitcnt vmcnt(16)
	v_pk_mul_f32 v[32:33], v[32:33], v[148:149] op_sel_hi:[1,0]
	v_pk_mul_f32 v[34:35], v[34:35], v[148:149] op_sel_hi:[1,0]
	v_pk_add_f32 v[116:117], v[116:117], 1.0 op_sel_hi:[1,0]
	v_pk_add_f32 v[118:119], v[118:119], 1.0 op_sel_hi:[1,0]
	v_pk_mul_f32 v[32:33], v[0:1], v[32:33]
	v_pk_mul_f32 v[34:35], v[2:3], v[34:35]
	v_pk_fma_f32 v[32:33], v[32:33], v[116:117], v[132:133]
	v_pk_fma_f32 v[34:35], v[34:35], v[118:119], v[134:135]
	v_cvt_pk_bf16_f32 v32, v32, v33
	v_cvt_pk_bf16_f32 v33, v34, v35
	global_store_dwordx2 v48, v[32:33], s[14:15]
	v_pk_mul_f32 v[36:37], v[36:37], v[148:149] op_sel_hi:[1,0]
	v_pk_mul_f32 v[38:39], v[38:39], v[148:149] op_sel_hi:[1,0]
	v_pk_add_f32 v[120:121], v[120:121], 1.0 op_sel_hi:[1,0]
	v_pk_add_f32 v[122:123], v[122:123], 1.0 op_sel_hi:[1,0]
	v_pk_mul_f32 v[36:37], v[4:5], v[36:37]
	v_pk_mul_f32 v[38:39], v[6:7], v[38:39]
	v_pk_fma_f32 v[36:37], v[36:37], v[120:121], v[136:137]
	v_pk_fma_f32 v[38:39], v[38:39], v[122:123], v[138:139]
	v_cvt_pk_bf16_f32 v36, v36, v37
	v_cvt_pk_bf16_f32 v37, v38, v39
	global_store_dwordx2 v48, v[36:37], s[14:15] offset:512
	v_pk_mul_f32 v[40:41], v[40:41], v[148:149] op_sel_hi:[1,0]
	v_pk_mul_f32 v[42:43], v[42:43], v[148:149] op_sel_hi:[1,0]
	v_pk_add_f32 v[124:125], v[124:125], 1.0 op_sel_hi:[1,0]
	v_pk_add_f32 v[126:127], v[126:127], 1.0 op_sel_hi:[1,0]
	v_pk_mul_f32 v[40:41], v[8:9], v[40:41]
	v_pk_mul_f32 v[42:43], v[10:11], v[42:43]
	v_pk_fma_f32 v[40:41], v[40:41], v[124:125], v[140:141]
	v_pk_fma_f32 v[42:43], v[42:43], v[126:127], v[142:143]
	v_cvt_pk_bf16_f32 v40, v40, v41
	v_cvt_pk_bf16_f32 v41, v42, v43
	global_store_dwordx2 v48, v[40:41], s[14:15] offset:1024
	v_pk_mul_f32 v[44:45], v[44:45], v[148:149] op_sel_hi:[1,0]
	v_pk_mul_f32 v[46:47], v[46:47], v[148:149] op_sel_hi:[1,0]
	v_pk_add_f32 v[128:129], v[128:129], 1.0 op_sel_hi:[1,0]
	v_pk_add_f32 v[130:131], v[130:131], 1.0 op_sel_hi:[1,0]
	v_pk_mul_f32 v[44:45], v[12:13], v[44:45]
	v_pk_mul_f32 v[46:47], v[14:15], v[46:47]
	v_pk_fma_f32 v[44:45], v[44:45], v[128:129], v[144:145]
	v_pk_fma_f32 v[46:47], v[46:47], v[130:131], v[146:147]
	v_cvt_pk_bf16_f32 v44, v44, v45
	v_cvt_pk_bf16_f32 v45, v46, v47
	global_store_dwordx2 v48, v[44:45], s[14:15] offset:1536
	s_add_u32 s14, s14, 0x400000
	s_addc_u32 s15, s15, 0
	global_load_dwordx4 v[32:35], v56, s[0:1] nt
	global_load_dwordx4 v[36:39], v56, s[0:1] offset:1024 nt
	global_load_dwordx4 v[40:43], v56, s[0:1] offset:2048 nt
	global_load_dwordx4 v[44:47], v56, s[0:1] offset:3072 nt
	s_add_u32 s0, s0, 0x800000
	s_addc_u32 s1, s1, 0
	global_load_dwordx4 v[132:135], v56, s[10:11]
	global_load_dwordx4 v[136:139], v56, s[10:11] offset:1024
	global_load_dwordx4 v[140:143], v56, s[10:11] offset:2048
	global_load_dwordx4 v[144:147], v56, s[10:11] offset:3072
	global_load_dwordx4 v[116:119], v56, s[12:13]
	global_load_dwordx4 v[120:123], v56, s[12:13] offset:1024
	global_load_dwordx4 v[124:127], v56, s[12:13] offset:2048
	global_load_dwordx4 v[128:131], v56, s[12:13] offset:3072
	s_add_u32 s10, s10, 0x6000
	s_addc_u32 s11, s11, 0
	s_add_u32 s12, s12, 0x6000
	s_addc_u32 s13, s13, 0
	s_waitcnt vmcnt(40)
	v_pk_mul_f32 v[58:59], v[68:69], v[68:69]
	v_pk_fma_f32 v[58:59], v[70:71], v[70:71], v[58:59]
	v_pk_fma_f32 v[58:59], v[72:73], v[72:73], v[58:59]
	v_pk_fma_f32 v[58:59], v[74:75], v[74:75], v[58:59]
	v_pk_fma_f32 v[58:59], v[76:77], v[76:77], v[58:59]
	v_pk_fma_f32 v[58:59], v[78:79], v[78:79], v[58:59]
	v_pk_fma_f32 v[58:59], v[80:81], v[80:81], v[58:59]
	v_pk_fma_f32 v[58:59], v[82:83], v[82:83], v[58:59]
	v_add_f32_e32 v60, v58, v59
	s_nop 1
	v_add_f32_dpp v61, v60, v60 quad_perm:[1,0,3,2] row_mask:0xf bank_mask:0xf
	s_nop 1
	v_add_f32_dpp v60, v61, v61 quad_perm:[2,3,0,1] row_mask:0xf bank_mask:0xf
	s_nop 1
	v_add_f32_dpp v61, v60, v60 row_half_mirror row_mask:0xf bank_mask:0xf
	s_nop 1
	v_add_f32_dpp v60, v61, v61 row_mirror row_mask:0xf bank_mask:0xf
	v_mov_b32_e32 v61, v60
	s_nop 1
	v_add_f32_dpp v61, v60, v60 row_bcast:15 row_mask:0xa bank_mask:0xf
	s_nop 1
	v_mov_b32_e32 v60, v61
	s_nop 1
	v_add_f32_dpp v60, v61, v61 row_bcast:31 row_mask:0xc bank_mask:0xf
	s_nop 1
	v_readlane_b32 s16, v60, 63
	s_nop 1
	v_mov_b32_e32 v148, s16
	v_fmamk_f32 v148, v148, 0x3a800000, v66
	v_rsq_f32_e32 v148, v148
	s_nop 0
	s_waitcnt vmcnt(16)
	v_pk_mul_f32 v[68:69], v[68:69], v[148:149] op_sel_hi:[1,0]
	v_pk_mul_f32 v[70:71], v[70:71], v[148:149] op_sel_hi:[1,0]
	v_pk_add_f32 v[84:85], v[84:85], 1.0 op_sel_hi:[1,0]
	v_pk_add_f32 v[86:87], v[86:87], 1.0 op_sel_hi:[1,0]
	v_pk_mul_f32 v[68:69], v[0:1], v[68:69]
	v_pk_mul_f32 v[70:71], v[2:3], v[70:71]
	v_pk_fma_f32 v[68:69], v[68:69], v[84:85], v[100:101]
	v_pk_fma_f32 v[70:71], v[70:71], v[86:87], v[102:103]
	v_cvt_pk_bf16_f32 v68, v68, v69
	v_cvt_pk_bf16_f32 v69, v70, v71
	global_store_dwordx2 v48, v[68:69], s[14:15]
	v_pk_mul_f32 v[72:73], v[72:73], v[148:149] op_sel_hi:[1,0]
	v_pk_mul_f32 v[74:75], v[74:75], v[148:149] op_sel_hi:[1,0]
	v_pk_add_f32 v[88:89], v[88:89], 1.0 op_sel_hi:[1,0]
	v_pk_add_f32 v[90:91], v[90:91], 1.0 op_sel_hi:[1,0]
	v_pk_mul_f32 v[72:73], v[4:5], v[72:73]
	v_pk_mul_f32 v[74:75], v[6:7], v[74:75]
	v_pk_fma_f32 v[72:73], v[72:73], v[88:89], v[104:105]
	v_pk_fma_f32 v[74:75], v[74:75], v[90:91], v[106:107]
	v_cvt_pk_bf16_f32 v72, v72, v73
	v_cvt_pk_bf16_f32 v73, v74, v75
	global_store_dwordx2 v48, v[72:73], s[14:15] offset:512
	v_pk_mul_f32 v[76:77], v[76:77], v[148:149] op_sel_hi:[1,0]
	v_pk_mul_f32 v[78:79], v[78:79], v[148:149] op_sel_hi:[1,0]
	v_pk_add_f32 v[92:93], v[92:93], 1.0 op_sel_hi:[1,0]
	v_pk_add_f32 v[94:95], v[94:95], 1.0 op_sel_hi:[1,0]
	v_pk_mul_f32 v[76:77], v[8:9], v[76:77]
	v_pk_mul_f32 v[78:79], v[10:11], v[78:79]
	v_pk_fma_f32 v[76:77], v[76:77], v[92:93], v[108:109]
	v_pk_fma_f32 v[78:79], v[78:79], v[94:95], v[110:111]
	v_cvt_pk_bf16_f32 v76, v76, v77
	v_cvt_pk_bf16_f32 v77, v78, v79
	global_store_dwordx2 v48, v[76:77], s[14:15] offset:1024
	v_pk_mul_f32 v[80:81], v[80:81], v[148:149] op_sel_hi:[1,0]
	v_pk_mul_f32 v[82:83], v[82:83], v[148:149] op_sel_hi:[1,0]
	v_pk_add_f32 v[96:97], v[96:97], 1.0 op_sel_hi:[1,0]
	v_pk_add_f32 v[98:99], v[98:99], 1.0 op_sel_hi:[1,0]
	v_pk_mul_f32 v[80:81], v[12:13], v[80:81]
	v_pk_mul_f32 v[82:83], v[14:15], v[82:83]
	v_pk_fma_f32 v[80:81], v[80:81], v[96:97], v[112:113]
	v_pk_fma_f32 v[82:83], v[82:83], v[98:99], v[114:115]
	v_cvt_pk_bf16_f32 v80, v80, v81
	v_cvt_pk_bf16_f32 v81, v82, v83
	global_store_dwordx2 v48, v[80:81], s[14:15] offset:1536
	s_add_u32 s14, s14, 0x400000
	s_addc_u32 s15, s15, 0
	global_load_dwordx4 v[68:71], v56, s[0:1] nt
	global_load_dwordx4 v[72:75], v56, s[0:1] offset:1024 nt
	global_load_dwordx4 v[76:79], v56, s[0:1] offset:2048 nt
	global_load_dwordx4 v[80:83], v56, s[0:1] offset:3072 nt
	s_add_u32 s0, s0, 0x800000
	s_addc_u32 s1, s1, 0
	global_load_dwordx4 v[100:103], v56, s[10:11]
	global_load_dwordx4 v[104:107], v56, s[10:11] offset:1024
	global_load_dwordx4 v[108:111], v56, s[10:11] offset:2048
	global_load_dwordx4 v[112:115], v56, s[10:11] offset:3072
	global_load_dwordx4 v[84:87], v56, s[12:13]
	global_load_dwordx4 v[88:91], v56, s[12:13] offset:1024
	global_load_dwordx4 v[92:95], v56, s[12:13] offset:2048
	global_load_dwordx4 v[96:99], v56, s[12:13] offset:3072
	s_add_u32 s10, s10, 0x6000
	s_addc_u32 s11, s11, 0
	s_add_u32 s12, s12, 0x6000
	s_addc_u32 s13, s13, 0
	s_waitcnt vmcnt(40)
	v_pk_mul_f32 v[58:59], v[16:17], v[16:17]
	v_pk_fma_f32 v[58:59], v[18:19], v[18:19], v[58:59]
	v_pk_fma_f32 v[58:59], v[20:21], v[20:21], v[58:59]
	v_pk_fma_f32 v[58:59], v[22:23], v[22:23], v[58:59]
	v_pk_fma_f32 v[58:59], v[24:25], v[24:25], v[58:59]
	v_pk_fma_f32 v[58:59], v[26:27], v[26:27], v[58:59]
	v_pk_fma_f32 v[58:59], v[28:29], v[28:29], v[58:59]
	v_pk_fma_f32 v[58:59], v[30:31], v[30:31], v[58:59]
	v_add_f32_e32 v60, v58, v59
	s_nop 1
	v_add_f32_dpp v61, v60, v60 quad_perm:[1,0,3,2] row_mask:0xf bank_mask:0xf
	s_nop 1
	v_add_f32_dpp v60, v61, v61 quad_perm:[2,3,0,1] row_mask:0xf bank_mask:0xf
	s_nop 1
	v_add_f32_dpp v61, v60, v60 row_half_mirror row_mask:0xf bank_mask:0xf
	s_nop 1
	v_add_f32_dpp v60, v61, v61 row_mirror row_mask:0xf bank_mask:0xf
	v_mov_b32_e32 v61, v60
	s_nop 1
	v_add_f32_dpp v61, v60, v60 row_bcast:15 row_mask:0xa bank_mask:0xf
	s_nop 1
	v_mov_b32_e32 v60, v61
	s_nop 1
	v_add_f32_dpp v60, v61, v61 row_bcast:31 row_mask:0xc bank_mask:0xf
	s_nop 1
	v_readlane_b32 s16, v60, 63
	s_nop 1
	v_mov_b32_e32 v148, s16
	v_fmamk_f32 v148, v148, 0x3a800000, v66
	v_rsq_f32_e32 v148, v148
	s_nop 0
	s_waitcnt vmcnt(16)
	v_pk_mul_f32 v[16:17], v[16:17], v[148:149] op_sel_hi:[1,0]
	v_pk_mul_f32 v[18:19], v[18:19], v[148:149] op_sel_hi:[1,0]
	v_pk_add_f32 v[116:117], v[116:117], 1.0 op_sel_hi:[1,0]
	v_pk_add_f32 v[118:119], v[118:119], 1.0 op_sel_hi:[1,0]
	v_pk_mul_f32 v[16:17], v[0:1], v[16:17]
	v_pk_mul_f32 v[18:19], v[2:3], v[18:19]
	v_pk_fma_f32 v[16:17], v[16:17], v[116:117], v[132:133]
	v_pk_fma_f32 v[18:19], v[18:19], v[118:119], v[134:135]
	v_cvt_pk_bf16_f32 v16, v16, v17
	v_cvt_pk_bf16_f32 v17, v18, v19
	global_store_dwordx2 v48, v[16:17], s[14:15]
	v_pk_mul_f32 v[20:21], v[20:21], v[148:149] op_sel_hi:[1,0]
	v_pk_mul_f32 v[22:23], v[22:23], v[148:149] op_sel_hi:[1,0]
	v_pk_add_f32 v[120:121], v[120:121], 1.0 op_sel_hi:[1,0]
	v_pk_add_f32 v[122:123], v[122:123], 1.0 op_sel_hi:[1,0]
	v_pk_mul_f32 v[20:21], v[4:5], v[20:21]
	v_pk_mul_f32 v[22:23], v[6:7], v[22:23]
	v_pk_fma_f32 v[20:21], v[20:21], v[120:121], v[136:137]
	v_pk_fma_f32 v[22:23], v[22:23], v[122:123], v[138:139]
	v_cvt_pk_bf16_f32 v20, v20, v21
	v_cvt_pk_bf16_f32 v21, v22, v23
	global_store_dwordx2 v48, v[20:21], s[14:15] offset:512
	v_pk_mul_f32 v[24:25], v[24:25], v[148:149] op_sel_hi:[1,0]
	v_pk_mul_f32 v[26:27], v[26:27], v[148:149] op_sel_hi:[1,0]
	v_pk_add_f32 v[124:125], v[124:125], 1.0 op_sel_hi:[1,0]
	v_pk_add_f32 v[126:127], v[126:127], 1.0 op_sel_hi:[1,0]
	v_pk_mul_f32 v[24:25], v[8:9], v[24:25]
	v_pk_mul_f32 v[26:27], v[10:11], v[26:27]
	v_pk_fma_f32 v[24:25], v[24:25], v[124:125], v[140:141]
	v_pk_fma_f32 v[26:27], v[26:27], v[126:127], v[142:143]
	v_cvt_pk_bf16_f32 v24, v24, v25
	v_cvt_pk_bf16_f32 v25, v26, v27
	global_store_dwordx2 v48, v[24:25], s[14:15] offset:1024
	v_pk_mul_f32 v[28:29], v[28:29], v[148:149] op_sel_hi:[1,0]
	v_pk_mul_f32 v[30:31], v[30:31], v[148:149] op_sel_hi:[1,0]
	v_pk_add_f32 v[128:129], v[128:129], 1.0 op_sel_hi:[1,0]
	v_pk_add_f32 v[130:131], v[130:131], 1.0 op_sel_hi:[1,0]
	v_pk_mul_f32 v[28:29], v[12:13], v[28:29]
	v_pk_mul_f32 v[30:31], v[14:15], v[30:31]
	v_pk_fma_f32 v[28:29], v[28:29], v[128:129], v[144:145]
	v_pk_fma_f32 v[30:31], v[30:31], v[130:131], v[146:147]
	v_cvt_pk_bf16_f32 v28, v28, v29
	v_cvt_pk_bf16_f32 v29, v30, v31
	global_store_dwordx2 v48, v[28:29], s[14:15] offset:1536
	s_add_u32 s14, s14, 0x400000
	s_addc_u32 s15, s15, 0
	global_load_dwordx4 v[16:19], v56, s[0:1] nt
	global_load_dwordx4 v[20:23], v56, s[0:1] offset:1024 nt
	global_load_dwordx4 v[24:27], v56, s[0:1] offset:2048 nt
	global_load_dwordx4 v[28:31], v56, s[0:1] offset:3072 nt
	s_add_u32 s0, s0, 0x800000
	s_addc_u32 s1, s1, 0
	global_load_dwordx4 v[132:135], v56, s[10:11]
	global_load_dwordx4 v[136:139], v56, s[10:11] offset:1024
	global_load_dwordx4 v[140:143], v56, s[10:11] offset:2048
	global_load_dwordx4 v[144:147], v56, s[10:11] offset:3072
	global_load_dwordx4 v[116:119], v56, s[12:13]
	global_load_dwordx4 v[120:123], v56, s[12:13] offset:1024
	global_load_dwordx4 v[124:127], v56, s[12:13] offset:2048
	global_load_dwordx4 v[128:131], v56, s[12:13] offset:3072
	s_add_u32 s10, s10, 0x6000
	s_addc_u32 s11, s11, 0
	s_add_u32 s12, s12, 0x6000
	s_addc_u32 s13, s13, 0
	s_waitcnt vmcnt(40)
	v_pk_mul_f32 v[58:59], v[32:33], v[32:33]
	v_pk_fma_f32 v[58:59], v[34:35], v[34:35], v[58:59]
	v_pk_fma_f32 v[58:59], v[36:37], v[36:37], v[58:59]
	v_pk_fma_f32 v[58:59], v[38:39], v[38:39], v[58:59]
	v_pk_fma_f32 v[58:59], v[40:41], v[40:41], v[58:59]
	v_pk_fma_f32 v[58:59], v[42:43], v[42:43], v[58:59]
	v_pk_fma_f32 v[58:59], v[44:45], v[44:45], v[58:59]
	v_pk_fma_f32 v[58:59], v[46:47], v[46:47], v[58:59]
	v_add_f32_e32 v60, v58, v59
	s_nop 1
	v_add_f32_dpp v61, v60, v60 quad_perm:[1,0,3,2] row_mask:0xf bank_mask:0xf
	s_nop 1
	v_add_f32_dpp v60, v61, v61 quad_perm:[2,3,0,1] row_mask:0xf bank_mask:0xf
	s_nop 1
	v_add_f32_dpp v61, v60, v60 row_half_mirror row_mask:0xf bank_mask:0xf
	s_nop 1
	v_add_f32_dpp v60, v61, v61 row_mirror row_mask:0xf bank_mask:0xf
	v_mov_b32_e32 v61, v60
	s_nop 1
	v_add_f32_dpp v61, v60, v60 row_bcast:15 row_mask:0xa bank_mask:0xf
	s_nop 1
	v_mov_b32_e32 v60, v61
	s_nop 1
	v_add_f32_dpp v60, v61, v61 row_bcast:31 row_mask:0xc bank_mask:0xf
	s_nop 1
	v_readlane_b32 s16, v60, 63
	s_nop 1
	v_mov_b32_e32 v148, s16
	v_fmamk_f32 v148, v148, 0x3a800000, v66
	v_rsq_f32_e32 v148, v148
	s_nop 0
	s_waitcnt vmcnt(16)
	v_pk_mul_f32 v[32:33], v[32:33], v[148:149] op_sel_hi:[1,0]
	v_pk_mul_f32 v[34:35], v[34:35], v[148:149] op_sel_hi:[1,0]
	v_pk_add_f32 v[84:85], v[84:85], 1.0 op_sel_hi:[1,0]
	v_pk_add_f32 v[86:87], v[86:87], 1.0 op_sel_hi:[1,0]
	v_pk_mul_f32 v[32:33], v[0:1], v[32:33]
	v_pk_mul_f32 v[34:35], v[2:3], v[34:35]
	v_pk_fma_f32 v[32:33], v[32:33], v[84:85], v[100:101]
	v_pk_fma_f32 v[34:35], v[34:35], v[86:87], v[102:103]
	v_cvt_pk_bf16_f32 v32, v32, v33
	v_cvt_pk_bf16_f32 v33, v34, v35
	global_store_dwordx2 v48, v[32:33], s[14:15]
	v_pk_mul_f32 v[36:37], v[36:37], v[148:149] op_sel_hi:[1,0]
	v_pk_mul_f32 v[38:39], v[38:39], v[148:149] op_sel_hi:[1,0]
	v_pk_add_f32 v[88:89], v[88:89], 1.0 op_sel_hi:[1,0]
	v_pk_add_f32 v[90:91], v[90:91], 1.0 op_sel_hi:[1,0]
	v_pk_mul_f32 v[36:37], v[4:5], v[36:37]
	v_pk_mul_f32 v[38:39], v[6:7], v[38:39]
	v_pk_fma_f32 v[36:37], v[36:37], v[88:89], v[104:105]
	v_pk_fma_f32 v[38:39], v[38:39], v[90:91], v[106:107]
	v_cvt_pk_bf16_f32 v36, v36, v37
	v_cvt_pk_bf16_f32 v37, v38, v39
	global_store_dwordx2 v48, v[36:37], s[14:15] offset:512
	v_pk_mul_f32 v[40:41], v[40:41], v[148:149] op_sel_hi:[1,0]
	v_pk_mul_f32 v[42:43], v[42:43], v[148:149] op_sel_hi:[1,0]
	v_pk_add_f32 v[92:93], v[92:93], 1.0 op_sel_hi:[1,0]
	v_pk_add_f32 v[94:95], v[94:95], 1.0 op_sel_hi:[1,0]
	v_pk_mul_f32 v[40:41], v[8:9], v[40:41]
	v_pk_mul_f32 v[42:43], v[10:11], v[42:43]
	v_pk_fma_f32 v[40:41], v[40:41], v[92:93], v[108:109]
	v_pk_fma_f32 v[42:43], v[42:43], v[94:95], v[110:111]
	v_cvt_pk_bf16_f32 v40, v40, v41
	v_cvt_pk_bf16_f32 v41, v42, v43
	global_store_dwordx2 v48, v[40:41], s[14:15] offset:1024
	v_pk_mul_f32 v[44:45], v[44:45], v[148:149] op_sel_hi:[1,0]
	v_pk_mul_f32 v[46:47], v[46:47], v[148:149] op_sel_hi:[1,0]
	v_pk_add_f32 v[96:97], v[96:97], 1.0 op_sel_hi:[1,0]
	v_pk_add_f32 v[98:99], v[98:99], 1.0 op_sel_hi:[1,0]
	v_pk_mul_f32 v[44:45], v[12:13], v[44:45]
	v_pk_mul_f32 v[46:47], v[14:15], v[46:47]
	v_pk_fma_f32 v[44:45], v[44:45], v[96:97], v[112:113]
	v_pk_fma_f32 v[46:47], v[46:47], v[98:99], v[114:115]
	v_cvt_pk_bf16_f32 v44, v44, v45
	v_cvt_pk_bf16_f32 v45, v46, v47
	global_store_dwordx2 v48, v[44:45], s[14:15] offset:1536
	s_add_u32 s14, s14, 0x400000
	s_addc_u32 s15, s15, 0
	global_load_dwordx4 v[32:35], v56, s[0:1] nt
	global_load_dwordx4 v[36:39], v56, s[0:1] offset:1024 nt
	global_load_dwordx4 v[40:43], v56, s[0:1] offset:2048 nt
	global_load_dwordx4 v[44:47], v56, s[0:1] offset:3072 nt
	s_add_u32 s0, s0, 0x800000
	s_addc_u32 s1, s1, 0
	global_load_dwordx4 v[100:103], v56, s[10:11]
	global_load_dwordx4 v[104:107], v56, s[10:11] offset:1024
	global_load_dwordx4 v[108:111], v56, s[10:11] offset:2048
	global_load_dwordx4 v[112:115], v56, s[10:11] offset:3072
	global_load_dwordx4 v[84:87], v56, s[12:13]
	global_load_dwordx4 v[88:91], v56, s[12:13] offset:1024
	global_load_dwordx4 v[92:95], v56, s[12:13] offset:2048
	global_load_dwordx4 v[96:99], v56, s[12:13] offset:3072
	s_add_u32 s10, s10, 0x6000
	s_addc_u32 s11, s11, 0
	s_add_u32 s12, s12, 0x6000
	s_addc_u32 s13, s13, 0
	s_waitcnt vmcnt(40)
	v_pk_mul_f32 v[58:59], v[68:69], v[68:69]
	v_pk_fma_f32 v[58:59], v[70:71], v[70:71], v[58:59]
	v_pk_fma_f32 v[58:59], v[72:73], v[72:73], v[58:59]
	v_pk_fma_f32 v[58:59], v[74:75], v[74:75], v[58:59]
	v_pk_fma_f32 v[58:59], v[76:77], v[76:77], v[58:59]
	v_pk_fma_f32 v[58:59], v[78:79], v[78:79], v[58:59]
	v_pk_fma_f32 v[58:59], v[80:81], v[80:81], v[58:59]
	v_pk_fma_f32 v[58:59], v[82:83], v[82:83], v[58:59]
	v_add_f32_e32 v60, v58, v59
	s_nop 1
	v_add_f32_dpp v61, v60, v60 quad_perm:[1,0,3,2] row_mask:0xf bank_mask:0xf
	s_nop 1
	v_add_f32_dpp v60, v61, v61 quad_perm:[2,3,0,1] row_mask:0xf bank_mask:0xf
	s_nop 1
	v_add_f32_dpp v61, v60, v60 row_half_mirror row_mask:0xf bank_mask:0xf
	s_nop 1
	v_add_f32_dpp v60, v61, v61 row_mirror row_mask:0xf bank_mask:0xf
	v_mov_b32_e32 v61, v60
	s_nop 1
	v_add_f32_dpp v61, v60, v60 row_bcast:15 row_mask:0xa bank_mask:0xf
	s_nop 1
	v_mov_b32_e32 v60, v61
	s_nop 1
	v_add_f32_dpp v60, v61, v61 row_bcast:31 row_mask:0xc bank_mask:0xf
	s_nop 1
	v_readlane_b32 s16, v60, 63
	s_nop 1
	v_mov_b32_e32 v148, s16
	v_fmamk_f32 v148, v148, 0x3a800000, v66
	v_rsq_f32_e32 v148, v148
	s_nop 0
	s_waitcnt vmcnt(16)
	v_pk_mul_f32 v[68:69], v[68:69], v[148:149] op_sel_hi:[1,0]
	v_pk_mul_f32 v[70:71], v[70:71], v[148:149] op_sel_hi:[1,0]
	v_pk_add_f32 v[116:117], v[116:117], 1.0 op_sel_hi:[1,0]
	v_pk_add_f32 v[118:119], v[118:119], 1.0 op_sel_hi:[1,0]
	v_pk_mul_f32 v[68:69], v[0:1], v[68:69]
	v_pk_mul_f32 v[70:71], v[2:3], v[70:71]
	v_pk_fma_f32 v[68:69], v[68:69], v[116:117], v[132:133]
	v_pk_fma_f32 v[70:71], v[70:71], v[118:119], v[134:135]
	v_cvt_pk_bf16_f32 v68, v68, v69
	v_cvt_pk_bf16_f32 v69, v70, v71
	global_store_dwordx2 v48, v[68:69], s[14:15]
	v_pk_mul_f32 v[72:73], v[72:73], v[148:149] op_sel_hi:[1,0]
	v_pk_mul_f32 v[74:75], v[74:75], v[148:149] op_sel_hi:[1,0]
	v_pk_add_f32 v[120:121], v[120:121], 1.0 op_sel_hi:[1,0]
	v_pk_add_f32 v[122:123], v[122:123], 1.0 op_sel_hi:[1,0]
	v_pk_mul_f32 v[72:73], v[4:5], v[72:73]
	v_pk_mul_f32 v[74:75], v[6:7], v[74:75]
	v_pk_fma_f32 v[72:73], v[72:73], v[120:121], v[136:137]
	v_pk_fma_f32 v[74:75], v[74:75], v[122:123], v[138:139]
	v_cvt_pk_bf16_f32 v72, v72, v73
	v_cvt_pk_bf16_f32 v73, v74, v75
	global_store_dwordx2 v48, v[72:73], s[14:15] offset:512
	v_pk_mul_f32 v[76:77], v[76:77], v[148:149] op_sel_hi:[1,0]
	v_pk_mul_f32 v[78:79], v[78:79], v[148:149] op_sel_hi:[1,0]
	v_pk_add_f32 v[124:125], v[124:125], 1.0 op_sel_hi:[1,0]
	v_pk_add_f32 v[126:127], v[126:127], 1.0 op_sel_hi:[1,0]
	v_pk_mul_f32 v[76:77], v[8:9], v[76:77]
	v_pk_mul_f32 v[78:79], v[10:11], v[78:79]
	v_pk_fma_f32 v[76:77], v[76:77], v[124:125], v[140:141]
	v_pk_fma_f32 v[78:79], v[78:79], v[126:127], v[142:143]
	v_cvt_pk_bf16_f32 v76, v76, v77
	v_cvt_pk_bf16_f32 v77, v78, v79
	global_store_dwordx2 v48, v[76:77], s[14:15] offset:1024
	v_pk_mul_f32 v[80:81], v[80:81], v[148:149] op_sel_hi:[1,0]
	v_pk_mul_f32 v[82:83], v[82:83], v[148:149] op_sel_hi:[1,0]
	v_pk_add_f32 v[128:129], v[128:129], 1.0 op_sel_hi:[1,0]
	v_pk_add_f32 v[130:131], v[130:131], 1.0 op_sel_hi:[1,0]
	v_pk_mul_f32 v[80:81], v[12:13], v[80:81]
	v_pk_mul_f32 v[82:83], v[14:15], v[82:83]
	v_pk_fma_f32 v[80:81], v[80:81], v[128:129], v[144:145]
	v_pk_fma_f32 v[82:83], v[82:83], v[130:131], v[146:147]
	v_cvt_pk_bf16_f32 v80, v80, v81
	v_cvt_pk_bf16_f32 v81, v82, v83
	global_store_dwordx2 v48, v[80:81], s[14:15] offset:1536
	s_add_u32 s14, s14, 0x400000
	s_addc_u32 s15, s15, 0
	global_load_dwordx4 v[68:71], v56, s[0:1] nt
	global_load_dwordx4 v[72:75], v56, s[0:1] offset:1024 nt
	global_load_dwordx4 v[76:79], v56, s[0:1] offset:2048 nt
	global_load_dwordx4 v[80:83], v56, s[0:1] offset:3072 nt
	s_add_u32 s0, s0, 0x800000
	s_addc_u32 s1, s1, 0
	global_load_dwordx4 v[132:135], v56, s[10:11]
	global_load_dwordx4 v[136:139], v56, s[10:11] offset:1024
	global_load_dwordx4 v[140:143], v56, s[10:11] offset:2048
	global_load_dwordx4 v[144:147], v56, s[10:11] offset:3072
	global_load_dwordx4 v[116:119], v56, s[12:13]
	global_load_dwordx4 v[120:123], v56, s[12:13] offset:1024
	global_load_dwordx4 v[124:127], v56, s[12:13] offset:2048
	global_load_dwordx4 v[128:131], v56, s[12:13] offset:3072
	s_add_u32 s10, s10, 0x6000
	s_addc_u32 s11, s11, 0
	s_add_u32 s12, s12, 0x6000
	s_addc_u32 s13, s13, 0
	s_waitcnt vmcnt(40)
	v_pk_mul_f32 v[58:59], v[16:17], v[16:17]
	v_pk_fma_f32 v[58:59], v[18:19], v[18:19], v[58:59]
	v_pk_fma_f32 v[58:59], v[20:21], v[20:21], v[58:59]
	v_pk_fma_f32 v[58:59], v[22:23], v[22:23], v[58:59]
	v_pk_fma_f32 v[58:59], v[24:25], v[24:25], v[58:59]
	v_pk_fma_f32 v[58:59], v[26:27], v[26:27], v[58:59]
	v_pk_fma_f32 v[58:59], v[28:29], v[28:29], v[58:59]
	v_pk_fma_f32 v[58:59], v[30:31], v[30:31], v[58:59]
	v_add_f32_e32 v60, v58, v59
	s_nop 1
	v_add_f32_dpp v61, v60, v60 quad_perm:[1,0,3,2] row_mask:0xf bank_mask:0xf
	s_nop 1
	v_add_f32_dpp v60, v61, v61 quad_perm:[2,3,0,1] row_mask:0xf bank_mask:0xf
	s_nop 1
	v_add_f32_dpp v61, v60, v60 row_half_mirror row_mask:0xf bank_mask:0xf
	s_nop 1
	v_add_f32_dpp v60, v61, v61 row_mirror row_mask:0xf bank_mask:0xf
	v_mov_b32_e32 v61, v60
	s_nop 1
	v_add_f32_dpp v61, v60, v60 row_bcast:15 row_mask:0xa bank_mask:0xf
	s_nop 1
	v_mov_b32_e32 v60, v61
	s_nop 1
	v_add_f32_dpp v60, v61, v61 row_bcast:31 row_mask:0xc bank_mask:0xf
	s_nop 1
	v_readlane_b32 s16, v60, 63
	s_nop 1
	v_mov_b32_e32 v148, s16
	v_fmamk_f32 v148, v148, 0x3a800000, v66
	v_rsq_f32_e32 v148, v148
	s_nop 0
	s_waitcnt vmcnt(16)
	v_pk_mul_f32 v[16:17], v[16:17], v[148:149] op_sel_hi:[1,0]
	v_pk_mul_f32 v[18:19], v[18:19], v[148:149] op_sel_hi:[1,0]
	v_pk_add_f32 v[84:85], v[84:85], 1.0 op_sel_hi:[1,0]
	v_pk_add_f32 v[86:87], v[86:87], 1.0 op_sel_hi:[1,0]
	v_pk_mul_f32 v[16:17], v[0:1], v[16:17]
	v_pk_mul_f32 v[18:19], v[2:3], v[18:19]
	v_pk_fma_f32 v[16:17], v[16:17], v[84:85], v[100:101]
	v_pk_fma_f32 v[18:19], v[18:19], v[86:87], v[102:103]
	v_cvt_pk_bf16_f32 v16, v16, v17
	v_cvt_pk_bf16_f32 v17, v18, v19
	global_store_dwordx2 v48, v[16:17], s[14:15]
	v_pk_mul_f32 v[20:21], v[20:21], v[148:149] op_sel_hi:[1,0]
	v_pk_mul_f32 v[22:23], v[22:23], v[148:149] op_sel_hi:[1,0]
	v_pk_add_f32 v[88:89], v[88:89], 1.0 op_sel_hi:[1,0]
	v_pk_add_f32 v[90:91], v[90:91], 1.0 op_sel_hi:[1,0]
	v_pk_mul_f32 v[20:21], v[4:5], v[20:21]
	v_pk_mul_f32 v[22:23], v[6:7], v[22:23]
	v_pk_fma_f32 v[20:21], v[20:21], v[88:89], v[104:105]
	v_pk_fma_f32 v[22:23], v[22:23], v[90:91], v[106:107]
	v_cvt_pk_bf16_f32 v20, v20, v21
	v_cvt_pk_bf16_f32 v21, v22, v23
	global_store_dwordx2 v48, v[20:21], s[14:15] offset:512
	v_pk_mul_f32 v[24:25], v[24:25], v[148:149] op_sel_hi:[1,0]
	v_pk_mul_f32 v[26:27], v[26:27], v[148:149] op_sel_hi:[1,0]
	v_pk_add_f32 v[92:93], v[92:93], 1.0 op_sel_hi:[1,0]
	v_pk_add_f32 v[94:95], v[94:95], 1.0 op_sel_hi:[1,0]
	v_pk_mul_f32 v[24:25], v[8:9], v[24:25]
	v_pk_mul_f32 v[26:27], v[10:11], v[26:27]
	v_pk_fma_f32 v[24:25], v[24:25], v[92:93], v[108:109]
	v_pk_fma_f32 v[26:27], v[26:27], v[94:95], v[110:111]
	v_cvt_pk_bf16_f32 v24, v24, v25
	v_cvt_pk_bf16_f32 v25, v26, v27
	global_store_dwordx2 v48, v[24:25], s[14:15] offset:1024
	v_pk_mul_f32 v[28:29], v[28:29], v[148:149] op_sel_hi:[1,0]
	v_pk_mul_f32 v[30:31], v[30:31], v[148:149] op_sel_hi:[1,0]
	v_pk_add_f32 v[96:97], v[96:97], 1.0 op_sel_hi:[1,0]
	v_pk_add_f32 v[98:99], v[98:99], 1.0 op_sel_hi:[1,0]
	v_pk_mul_f32 v[28:29], v[12:13], v[28:29]
	v_pk_mul_f32 v[30:31], v[14:15], v[30:31]
	v_pk_fma_f32 v[28:29], v[28:29], v[96:97], v[112:113]
	v_pk_fma_f32 v[30:31], v[30:31], v[98:99], v[114:115]
	v_cvt_pk_bf16_f32 v28, v28, v29
	v_cvt_pk_bf16_f32 v29, v30, v31
	global_store_dwordx2 v48, v[28:29], s[14:15] offset:1536
	s_add_u32 s14, s14, 0x400000
	s_addc_u32 s15, s15, 0
	global_load_dwordx4 v[16:19], v56, s[0:1] nt
	global_load_dwordx4 v[20:23], v56, s[0:1] offset:1024 nt
	global_load_dwordx4 v[24:27], v56, s[0:1] offset:2048 nt
	global_load_dwordx4 v[28:31], v56, s[0:1] offset:3072 nt
	s_add_u32 s0, s0, 0x800000
	s_addc_u32 s1, s1, 0
	global_load_dwordx4 v[100:103], v56, s[10:11]
	global_load_dwordx4 v[104:107], v56, s[10:11] offset:1024
	global_load_dwordx4 v[108:111], v56, s[10:11] offset:2048
	global_load_dwordx4 v[112:115], v56, s[10:11] offset:3072
	global_load_dwordx4 v[84:87], v56, s[12:13]
	global_load_dwordx4 v[88:91], v56, s[12:13] offset:1024
	global_load_dwordx4 v[92:95], v56, s[12:13] offset:2048
	global_load_dwordx4 v[96:99], v56, s[12:13] offset:3072
	s_add_u32 s10, s10, 0x6000
	s_addc_u32 s11, s11, 0
	s_add_u32 s12, s12, 0x6000
	s_addc_u32 s13, s13, 0
	s_waitcnt vmcnt(40)
	v_pk_mul_f32 v[58:59], v[32:33], v[32:33]
	v_pk_fma_f32 v[58:59], v[34:35], v[34:35], v[58:59]
	v_pk_fma_f32 v[58:59], v[36:37], v[36:37], v[58:59]
	v_pk_fma_f32 v[58:59], v[38:39], v[38:39], v[58:59]
	v_pk_fma_f32 v[58:59], v[40:41], v[40:41], v[58:59]
	v_pk_fma_f32 v[58:59], v[42:43], v[42:43], v[58:59]
	v_pk_fma_f32 v[58:59], v[44:45], v[44:45], v[58:59]
	v_pk_fma_f32 v[58:59], v[46:47], v[46:47], v[58:59]
	v_add_f32_e32 v60, v58, v59
	s_nop 1
	v_add_f32_dpp v61, v60, v60 quad_perm:[1,0,3,2] row_mask:0xf bank_mask:0xf
	s_nop 1
	v_add_f32_dpp v60, v61, v61 quad_perm:[2,3,0,1] row_mask:0xf bank_mask:0xf
	s_nop 1
	v_add_f32_dpp v61, v60, v60 row_half_mirror row_mask:0xf bank_mask:0xf
	s_nop 1
	v_add_f32_dpp v60, v61, v61 row_mirror row_mask:0xf bank_mask:0xf
	v_mov_b32_e32 v61, v60
	s_nop 1
	v_add_f32_dpp v61, v60, v60 row_bcast:15 row_mask:0xa bank_mask:0xf
	s_nop 1
	v_mov_b32_e32 v60, v61
	s_nop 1
	v_add_f32_dpp v60, v61, v61 row_bcast:31 row_mask:0xc bank_mask:0xf
	s_nop 1
	v_readlane_b32 s16, v60, 63
	s_nop 1
	v_mov_b32_e32 v148, s16
	v_fmamk_f32 v148, v148, 0x3a800000, v66
	v_rsq_f32_e32 v148, v148
	s_nop 0
	s_waitcnt vmcnt(16)
	v_pk_mul_f32 v[32:33], v[32:33], v[148:149] op_sel_hi:[1,0]
	v_pk_mul_f32 v[34:35], v[34:35], v[148:149] op_sel_hi:[1,0]
	v_pk_add_f32 v[116:117], v[116:117], 1.0 op_sel_hi:[1,0]
	v_pk_add_f32 v[118:119], v[118:119], 1.0 op_sel_hi:[1,0]
	v_pk_mul_f32 v[32:33], v[0:1], v[32:33]
	v_pk_mul_f32 v[34:35], v[2:3], v[34:35]
	v_pk_fma_f32 v[32:33], v[32:33], v[116:117], v[132:133]
	v_pk_fma_f32 v[34:35], v[34:35], v[118:119], v[134:135]
	v_cvt_pk_bf16_f32 v32, v32, v33
	v_cvt_pk_bf16_f32 v33, v34, v35
	global_store_dwordx2 v48, v[32:33], s[14:15]
	v_pk_mul_f32 v[36:37], v[36:37], v[148:149] op_sel_hi:[1,0]
	v_pk_mul_f32 v[38:39], v[38:39], v[148:149] op_sel_hi:[1,0]
	v_pk_add_f32 v[120:121], v[120:121], 1.0 op_sel_hi:[1,0]
	v_pk_add_f32 v[122:123], v[122:123], 1.0 op_sel_hi:[1,0]
	v_pk_mul_f32 v[36:37], v[4:5], v[36:37]
	v_pk_mul_f32 v[38:39], v[6:7], v[38:39]
	v_pk_fma_f32 v[36:37], v[36:37], v[120:121], v[136:137]
	v_pk_fma_f32 v[38:39], v[38:39], v[122:123], v[138:139]
	v_cvt_pk_bf16_f32 v36, v36, v37
	v_cvt_pk_bf16_f32 v37, v38, v39
	global_store_dwordx2 v48, v[36:37], s[14:15] offset:512
	v_pk_mul_f32 v[40:41], v[40:41], v[148:149] op_sel_hi:[1,0]
	v_pk_mul_f32 v[42:43], v[42:43], v[148:149] op_sel_hi:[1,0]
	v_pk_add_f32 v[124:125], v[124:125], 1.0 op_sel_hi:[1,0]
	v_pk_add_f32 v[126:127], v[126:127], 1.0 op_sel_hi:[1,0]
	v_pk_mul_f32 v[40:41], v[8:9], v[40:41]
	v_pk_mul_f32 v[42:43], v[10:11], v[42:43]
	v_pk_fma_f32 v[40:41], v[40:41], v[124:125], v[140:141]
	v_pk_fma_f32 v[42:43], v[42:43], v[126:127], v[142:143]
	v_cvt_pk_bf16_f32 v40, v40, v41
	v_cvt_pk_bf16_f32 v41, v42, v43
	global_store_dwordx2 v48, v[40:41], s[14:15] offset:1024
	v_pk_mul_f32 v[44:45], v[44:45], v[148:149] op_sel_hi:[1,0]
	v_pk_mul_f32 v[46:47], v[46:47], v[148:149] op_sel_hi:[1,0]
	v_pk_add_f32 v[128:129], v[128:129], 1.0 op_sel_hi:[1,0]
	v_pk_add_f32 v[130:131], v[130:131], 1.0 op_sel_hi:[1,0]
	v_pk_mul_f32 v[44:45], v[12:13], v[44:45]
	v_pk_mul_f32 v[46:47], v[14:15], v[46:47]
	v_pk_fma_f32 v[44:45], v[44:45], v[128:129], v[144:145]
	v_pk_fma_f32 v[46:47], v[46:47], v[130:131], v[146:147]
	v_cvt_pk_bf16_f32 v44, v44, v45
	v_cvt_pk_bf16_f32 v45, v46, v47
	global_store_dwordx2 v48, v[44:45], s[14:15] offset:1536
	s_add_u32 s14, s14, 0x400000
	s_addc_u32 s15, s15, 0
	v_readlane_b32 s0, v253, 14
	v_readlane_b32 s1, v253, 15
	s_lshl_b64 s[16:17], s[4:5], 12
	s_add_u32 s0, s0, s16
	s_addc_u32 s1, s1, s17
	global_load_dwordx4 v[32:35], v56, s[0:1] nt
	global_load_dwordx4 v[36:39], v56, s[0:1] offset:1024 nt
	global_load_dwordx4 v[40:43], v56, s[0:1] offset:2048 nt
	global_load_dwordx4 v[44:47], v56, s[0:1] offset:3072 nt
	s_add_u32 s0, s0, 0x800000
	s_addc_u32 s1, s1, 0
	global_load_dwordx4 v[132:135], v56, s[10:11]
	global_load_dwordx4 v[136:139], v56, s[10:11] offset:1024
	global_load_dwordx4 v[140:143], v56, s[10:11] offset:2048
	global_load_dwordx4 v[144:147], v56, s[10:11] offset:3072
	global_load_dwordx4 v[116:119], v56, s[12:13]
	global_load_dwordx4 v[120:123], v56, s[12:13] offset:1024
	global_load_dwordx4 v[124:127], v56, s[12:13] offset:2048
	global_load_dwordx4 v[128:131], v56, s[12:13] offset:3072
	s_add_u32 s10, s10, 0x6000
	s_addc_u32 s11, s11, 0
	s_add_u32 s12, s12, 0x6000
	s_addc_u32 s13, s13, 0
	s_waitcnt vmcnt(40)
	v_pk_mul_f32 v[58:59], v[68:69], v[68:69]
	v_pk_fma_f32 v[58:59], v[70:71], v[70:71], v[58:59]
	v_pk_fma_f32 v[58:59], v[72:73], v[72:73], v[58:59]
	v_pk_fma_f32 v[58:59], v[74:75], v[74:75], v[58:59]
	v_pk_fma_f32 v[58:59], v[76:77], v[76:77], v[58:59]
	v_pk_fma_f32 v[58:59], v[78:79], v[78:79], v[58:59]
	v_pk_fma_f32 v[58:59], v[80:81], v[80:81], v[58:59]
	v_pk_fma_f32 v[58:59], v[82:83], v[82:83], v[58:59]
	v_add_f32_e32 v60, v58, v59
	s_nop 1
	v_add_f32_dpp v61, v60, v60 quad_perm:[1,0,3,2] row_mask:0xf bank_mask:0xf
	s_nop 1
	v_add_f32_dpp v60, v61, v61 quad_perm:[2,3,0,1] row_mask:0xf bank_mask:0xf
	s_nop 1
	v_add_f32_dpp v61, v60, v60 row_half_mirror row_mask:0xf bank_mask:0xf
	s_nop 1
	v_add_f32_dpp v60, v61, v61 row_mirror row_mask:0xf bank_mask:0xf
	v_mov_b32_e32 v61, v60
	s_nop 1
	v_add_f32_dpp v61, v60, v60 row_bcast:15 row_mask:0xa bank_mask:0xf
	s_nop 1
	v_mov_b32_e32 v60, v61
	s_nop 1
	v_add_f32_dpp v60, v61, v61 row_bcast:31 row_mask:0xc bank_mask:0xf
	s_nop 1
	v_readlane_b32 s16, v60, 63
	s_nop 1
	v_mov_b32_e32 v148, s16
	v_fmamk_f32 v148, v148, 0x3a800000, v66
	v_rsq_f32_e32 v148, v148
	s_nop 0
	s_waitcnt vmcnt(16)
	v_pk_mul_f32 v[68:69], v[68:69], v[148:149] op_sel_hi:[1,0]
	v_pk_mul_f32 v[70:71], v[70:71], v[148:149] op_sel_hi:[1,0]
	v_pk_add_f32 v[84:85], v[84:85], 1.0 op_sel_hi:[1,0]
	v_pk_add_f32 v[86:87], v[86:87], 1.0 op_sel_hi:[1,0]
	v_pk_mul_f32 v[68:69], v[0:1], v[68:69]
	v_pk_mul_f32 v[70:71], v[2:3], v[70:71]
	v_pk_fma_f32 v[68:69], v[68:69], v[84:85], v[100:101]
	v_pk_fma_f32 v[70:71], v[70:71], v[86:87], v[102:103]
	v_cvt_pk_bf16_f32 v68, v68, v69
	v_cvt_pk_bf16_f32 v69, v70, v71
	global_store_dwordx2 v48, v[68:69], s[14:15]
	v_pk_mul_f32 v[72:73], v[72:73], v[148:149] op_sel_hi:[1,0]
	v_pk_mul_f32 v[74:75], v[74:75], v[148:149] op_sel_hi:[1,0]
	v_pk_add_f32 v[88:89], v[88:89], 1.0 op_sel_hi:[1,0]
	v_pk_add_f32 v[90:91], v[90:91], 1.0 op_sel_hi:[1,0]
	v_pk_mul_f32 v[72:73], v[4:5], v[72:73]
	v_pk_mul_f32 v[74:75], v[6:7], v[74:75]
	v_pk_fma_f32 v[72:73], v[72:73], v[88:89], v[104:105]
	v_pk_fma_f32 v[74:75], v[74:75], v[90:91], v[106:107]
	v_cvt_pk_bf16_f32 v72, v72, v73
	v_cvt_pk_bf16_f32 v73, v74, v75
	global_store_dwordx2 v48, v[72:73], s[14:15] offset:512
	v_pk_mul_f32 v[76:77], v[76:77], v[148:149] op_sel_hi:[1,0]
	v_pk_mul_f32 v[78:79], v[78:79], v[148:149] op_sel_hi:[1,0]
	v_pk_add_f32 v[92:93], v[92:93], 1.0 op_sel_hi:[1,0]
	v_pk_add_f32 v[94:95], v[94:95], 1.0 op_sel_hi:[1,0]
	v_pk_mul_f32 v[76:77], v[8:9], v[76:77]
	v_pk_mul_f32 v[78:79], v[10:11], v[78:79]
	v_pk_fma_f32 v[76:77], v[76:77], v[92:93], v[108:109]
	v_pk_fma_f32 v[78:79], v[78:79], v[94:95], v[110:111]
	v_cvt_pk_bf16_f32 v76, v76, v77
	v_cvt_pk_bf16_f32 v77, v78, v79
	global_store_dwordx2 v48, v[76:77], s[14:15] offset:1024
	v_pk_mul_f32 v[80:81], v[80:81], v[148:149] op_sel_hi:[1,0]
	v_pk_mul_f32 v[82:83], v[82:83], v[148:149] op_sel_hi:[1,0]
	v_pk_add_f32 v[96:97], v[96:97], 1.0 op_sel_hi:[1,0]
	v_pk_add_f32 v[98:99], v[98:99], 1.0 op_sel_hi:[1,0]
	v_pk_mul_f32 v[80:81], v[12:13], v[80:81]
	v_pk_mul_f32 v[82:83], v[14:15], v[82:83]
	v_pk_fma_f32 v[80:81], v[80:81], v[96:97], v[112:113]
	v_pk_fma_f32 v[82:83], v[82:83], v[98:99], v[114:115]
	v_cvt_pk_bf16_f32 v80, v80, v81
	v_cvt_pk_bf16_f32 v81, v82, v83
	global_store_dwordx2 v48, v[80:81], s[14:15] offset:1536
	s_add_u32 s14, s14, 0x400000
	s_addc_u32 s15, s15, 0
	global_load_dwordx4 v[68:71], v56, s[0:1] nt
	global_load_dwordx4 v[72:75], v56, s[0:1] offset:1024 nt
	global_load_dwordx4 v[76:79], v56, s[0:1] offset:2048 nt
	global_load_dwordx4 v[80:83], v56, s[0:1] offset:3072 nt
	s_add_u32 s0, s0, 0x800000
	s_addc_u32 s1, s1, 0
	global_load_dwordx4 v[100:103], v56, s[10:11]
	global_load_dwordx4 v[104:107], v56, s[10:11] offset:1024
	global_load_dwordx4 v[108:111], v56, s[10:11] offset:2048
	global_load_dwordx4 v[112:115], v56, s[10:11] offset:3072
	global_load_dwordx4 v[84:87], v56, s[12:13]
	global_load_dwordx4 v[88:91], v56, s[12:13] offset:1024
	global_load_dwordx4 v[92:95], v56, s[12:13] offset:2048
	global_load_dwordx4 v[96:99], v56, s[12:13] offset:3072
	s_waitcnt vmcnt(40)
	v_pk_mul_f32 v[58:59], v[16:17], v[16:17]
	v_pk_fma_f32 v[58:59], v[18:19], v[18:19], v[58:59]
	v_pk_fma_f32 v[58:59], v[20:21], v[20:21], v[58:59]
	v_pk_fma_f32 v[58:59], v[22:23], v[22:23], v[58:59]
	v_pk_fma_f32 v[58:59], v[24:25], v[24:25], v[58:59]
	v_pk_fma_f32 v[58:59], v[26:27], v[26:27], v[58:59]
	v_pk_fma_f32 v[58:59], v[28:29], v[28:29], v[58:59]
	v_pk_fma_f32 v[58:59], v[30:31], v[30:31], v[58:59]
	v_add_f32_e32 v60, v58, v59
	s_nop 1
	v_add_f32_dpp v61, v60, v60 quad_perm:[1,0,3,2] row_mask:0xf bank_mask:0xf
	s_nop 1
	v_add_f32_dpp v60, v61, v61 quad_perm:[2,3,0,1] row_mask:0xf bank_mask:0xf
	s_nop 1
	v_add_f32_dpp v61, v60, v60 row_half_mirror row_mask:0xf bank_mask:0xf
	s_nop 1
	v_add_f32_dpp v60, v61, v61 row_mirror row_mask:0xf bank_mask:0xf
	v_mov_b32_e32 v61, v60
	s_nop 1
	v_add_f32_dpp v61, v60, v60 row_bcast:15 row_mask:0xa bank_mask:0xf
	s_nop 1
	v_mov_b32_e32 v60, v61
	s_nop 1
	v_add_f32_dpp v60, v61, v61 row_bcast:31 row_mask:0xc bank_mask:0xf
	s_nop 1
	v_readlane_b32 s16, v60, 63
	s_nop 1
	v_mov_b32_e32 v148, s16
	v_fmamk_f32 v148, v148, 0x3a800000, v66
	v_rsq_f32_e32 v148, v148
	s_nop 0
	s_waitcnt vmcnt(16)
	v_pk_mul_f32 v[16:17], v[16:17], v[148:149] op_sel_hi:[1,0]
	v_pk_mul_f32 v[18:19], v[18:19], v[148:149] op_sel_hi:[1,0]
	v_pk_add_f32 v[116:117], v[116:117], 1.0 op_sel_hi:[1,0]
	v_pk_add_f32 v[118:119], v[118:119], 1.0 op_sel_hi:[1,0]
	v_pk_mul_f32 v[16:17], v[0:1], v[16:17]
	v_pk_mul_f32 v[18:19], v[2:3], v[18:19]
	v_pk_fma_f32 v[16:17], v[16:17], v[116:117], v[132:133]
	v_pk_fma_f32 v[18:19], v[18:19], v[118:119], v[134:135]
	v_cvt_pk_bf16_f32 v16, v16, v17
	v_cvt_pk_bf16_f32 v17, v18, v19
	global_store_dwordx2 v48, v[16:17], s[14:15]
	v_pk_mul_f32 v[20:21], v[20:21], v[148:149] op_sel_hi:[1,0]
	v_pk_mul_f32 v[22:23], v[22:23], v[148:149] op_sel_hi:[1,0]
	v_pk_add_f32 v[120:121], v[120:121], 1.0 op_sel_hi:[1,0]
	v_pk_add_f32 v[122:123], v[122:123], 1.0 op_sel_hi:[1,0]
	v_pk_mul_f32 v[20:21], v[4:5], v[20:21]
	v_pk_mul_f32 v[22:23], v[6:7], v[22:23]
	v_pk_fma_f32 v[20:21], v[20:21], v[120:121], v[136:137]
	v_pk_fma_f32 v[22:23], v[22:23], v[122:123], v[138:139]
	v_cvt_pk_bf16_f32 v20, v20, v21
	v_cvt_pk_bf16_f32 v21, v22, v23
	global_store_dwordx2 v48, v[20:21], s[14:15] offset:512
	v_pk_mul_f32 v[24:25], v[24:25], v[148:149] op_sel_hi:[1,0]
	v_pk_mul_f32 v[26:27], v[26:27], v[148:149] op_sel_hi:[1,0]
	v_pk_add_f32 v[124:125], v[124:125], 1.0 op_sel_hi:[1,0]
	v_pk_add_f32 v[126:127], v[126:127], 1.0 op_sel_hi:[1,0]
	v_pk_mul_f32 v[24:25], v[8:9], v[24:25]
	v_pk_mul_f32 v[26:27], v[10:11], v[26:27]
	v_pk_fma_f32 v[24:25], v[24:25], v[124:125], v[140:141]
	v_pk_fma_f32 v[26:27], v[26:27], v[126:127], v[142:143]
	v_cvt_pk_bf16_f32 v24, v24, v25
	v_cvt_pk_bf16_f32 v25, v26, v27
	global_store_dwordx2 v48, v[24:25], s[14:15] offset:1024
	v_pk_mul_f32 v[28:29], v[28:29], v[148:149] op_sel_hi:[1,0]
	v_pk_mul_f32 v[30:31], v[30:31], v[148:149] op_sel_hi:[1,0]
	v_pk_add_f32 v[128:129], v[128:129], 1.0 op_sel_hi:[1,0]
	v_pk_add_f32 v[130:131], v[130:131], 1.0 op_sel_hi:[1,0]
	v_pk_mul_f32 v[28:29], v[12:13], v[28:29]
	v_pk_mul_f32 v[30:31], v[14:15], v[30:31]
	v_pk_fma_f32 v[28:29], v[28:29], v[128:129], v[144:145]
	v_pk_fma_f32 v[30:31], v[30:31], v[130:131], v[146:147]
	v_cvt_pk_bf16_f32 v28, v28, v29
	v_cvt_pk_bf16_f32 v29, v30, v31
	global_store_dwordx2 v48, v[28:29], s[14:15] offset:1536
	s_add_u32 s14, s14, 0x400000
	s_addc_u32 s15, s15, 0
	global_load_dwordx4 v[132:135], v56, s[10:11]
	global_load_dwordx4 v[136:139], v56, s[10:11] offset:1024
	global_load_dwordx4 v[140:143], v56, s[10:11] offset:2048
	global_load_dwordx4 v[144:147], v56, s[10:11] offset:3072
	global_load_dwordx4 v[116:119], v56, s[12:13]
	global_load_dwordx4 v[120:123], v56, s[12:13] offset:1024
	global_load_dwordx4 v[124:127], v56, s[12:13] offset:2048
	global_load_dwordx4 v[128:131], v56, s[12:13] offset:3072
	s_waitcnt vmcnt(36)
	v_pk_mul_f32 v[58:59], v[32:33], v[32:33]
	v_pk_fma_f32 v[58:59], v[34:35], v[34:35], v[58:59]
	v_pk_fma_f32 v[58:59], v[36:37], v[36:37], v[58:59]
	v_pk_fma_f32 v[58:59], v[38:39], v[38:39], v[58:59]
	v_pk_fma_f32 v[58:59], v[40:41], v[40:41], v[58:59]
	v_pk_fma_f32 v[58:59], v[42:43], v[42:43], v[58:59]
	v_pk_fma_f32 v[58:59], v[44:45], v[44:45], v[58:59]
	v_pk_fma_f32 v[58:59], v[46:47], v[46:47], v[58:59]
	v_add_f32_e32 v60, v58, v59
	s_nop 1
	v_add_f32_dpp v61, v60, v60 quad_perm:[1,0,3,2] row_mask:0xf bank_mask:0xf
	s_nop 1
	v_add_f32_dpp v60, v61, v61 quad_perm:[2,3,0,1] row_mask:0xf bank_mask:0xf
	s_nop 1
	v_add_f32_dpp v61, v60, v60 row_half_mirror row_mask:0xf bank_mask:0xf
	s_nop 1
	v_add_f32_dpp v60, v61, v61 row_mirror row_mask:0xf bank_mask:0xf
	v_mov_b32_e32 v61, v60
	s_nop 1
	v_add_f32_dpp v61, v60, v60 row_bcast:15 row_mask:0xa bank_mask:0xf
	s_nop 1
	v_mov_b32_e32 v60, v61
	s_nop 1
	v_add_f32_dpp v60, v61, v61 row_bcast:31 row_mask:0xc bank_mask:0xf
	s_nop 1
	v_readlane_b32 s16, v60, 63
	s_nop 1
	v_mov_b32_e32 v148, s16
	v_fmamk_f32 v148, v148, 0x3a800000, v66
	v_rsq_f32_e32 v148, v148
	s_nop 0
	s_waitcnt vmcnt(12)
	v_pk_mul_f32 v[32:33], v[32:33], v[148:149] op_sel_hi:[1,0]
	v_pk_mul_f32 v[34:35], v[34:35], v[148:149] op_sel_hi:[1,0]
	v_pk_add_f32 v[84:85], v[84:85], 1.0 op_sel_hi:[1,0]
	v_pk_add_f32 v[86:87], v[86:87], 1.0 op_sel_hi:[1,0]
	v_pk_mul_f32 v[32:33], v[0:1], v[32:33]
	v_pk_mul_f32 v[34:35], v[2:3], v[34:35]
	v_pk_fma_f32 v[32:33], v[32:33], v[84:85], v[100:101]
	v_pk_fma_f32 v[34:35], v[34:35], v[86:87], v[102:103]
	v_cvt_pk_bf16_f32 v32, v32, v33
	v_cvt_pk_bf16_f32 v33, v34, v35
	global_store_dwordx2 v48, v[32:33], s[14:15]
	v_pk_mul_f32 v[36:37], v[36:37], v[148:149] op_sel_hi:[1,0]
	v_pk_mul_f32 v[38:39], v[38:39], v[148:149] op_sel_hi:[1,0]
	v_pk_add_f32 v[88:89], v[88:89], 1.0 op_sel_hi:[1,0]
	v_pk_add_f32 v[90:91], v[90:91], 1.0 op_sel_hi:[1,0]
	v_pk_mul_f32 v[36:37], v[4:5], v[36:37]
	v_pk_mul_f32 v[38:39], v[6:7], v[38:39]
	v_pk_fma_f32 v[36:37], v[36:37], v[88:89], v[104:105]
	v_pk_fma_f32 v[38:39], v[38:39], v[90:91], v[106:107]
	v_cvt_pk_bf16_f32 v36, v36, v37
	v_cvt_pk_bf16_f32 v37, v38, v39
	global_store_dwordx2 v48, v[36:37], s[14:15] offset:512
	v_pk_mul_f32 v[40:41], v[40:41], v[148:149] op_sel_hi:[1,0]
	v_pk_mul_f32 v[42:43], v[42:43], v[148:149] op_sel_hi:[1,0]
	v_pk_add_f32 v[92:93], v[92:93], 1.0 op_sel_hi:[1,0]
	v_pk_add_f32 v[94:95], v[94:95], 1.0 op_sel_hi:[1,0]
	v_pk_mul_f32 v[40:41], v[8:9], v[40:41]
	v_pk_mul_f32 v[42:43], v[10:11], v[42:43]
	v_pk_fma_f32 v[40:41], v[40:41], v[92:93], v[108:109]
	v_pk_fma_f32 v[42:43], v[42:43], v[94:95], v[110:111]
	v_cvt_pk_bf16_f32 v40, v40, v41
	v_cvt_pk_bf16_f32 v41, v42, v43
	global_store_dwordx2 v48, v[40:41], s[14:15] offset:1024
	v_pk_mul_f32 v[44:45], v[44:45], v[148:149] op_sel_hi:[1,0]
	v_pk_mul_f32 v[46:47], v[46:47], v[148:149] op_sel_hi:[1,0]
	v_pk_add_f32 v[96:97], v[96:97], 1.0 op_sel_hi:[1,0]
	v_pk_add_f32 v[98:99], v[98:99], 1.0 op_sel_hi:[1,0]
	v_pk_mul_f32 v[44:45], v[12:13], v[44:45]
	v_pk_mul_f32 v[46:47], v[14:15], v[46:47]
	v_pk_fma_f32 v[44:45], v[44:45], v[96:97], v[112:113]
	v_pk_fma_f32 v[46:47], v[46:47], v[98:99], v[114:115]
	v_cvt_pk_bf16_f32 v44, v44, v45
	v_cvt_pk_bf16_f32 v45, v46, v47
	global_store_dwordx2 v48, v[44:45], s[14:15] offset:1536
	s_add_u32 s14, s14, 0x400000
	s_addc_u32 s15, s15, 0
	s_waitcnt vmcnt(24)
	v_pk_mul_f32 v[58:59], v[68:69], v[68:69]
	v_pk_fma_f32 v[58:59], v[70:71], v[70:71], v[58:59]
	v_pk_fma_f32 v[58:59], v[72:73], v[72:73], v[58:59]
	v_pk_fma_f32 v[58:59], v[74:75], v[74:75], v[58:59]
	v_pk_fma_f32 v[58:59], v[76:77], v[76:77], v[58:59]
	v_pk_fma_f32 v[58:59], v[78:79], v[78:79], v[58:59]
	v_pk_fma_f32 v[58:59], v[80:81], v[80:81], v[58:59]
	v_pk_fma_f32 v[58:59], v[82:83], v[82:83], v[58:59]
	v_add_f32_e32 v60, v58, v59
	s_nop 1
	v_add_f32_dpp v61, v60, v60 quad_perm:[1,0,3,2] row_mask:0xf bank_mask:0xf
	s_nop 1
	v_add_f32_dpp v60, v61, v61 quad_perm:[2,3,0,1] row_mask:0xf bank_mask:0xf
	s_nop 1
	v_add_f32_dpp v61, v60, v60 row_half_mirror row_mask:0xf bank_mask:0xf
	s_nop 1
	v_add_f32_dpp v60, v61, v61 row_mirror row_mask:0xf bank_mask:0xf
	v_mov_b32_e32 v61, v60
	s_nop 1
	v_add_f32_dpp v61, v60, v60 row_bcast:15 row_mask:0xa bank_mask:0xf
	s_nop 1
	v_mov_b32_e32 v60, v61
	s_nop 1
	v_add_f32_dpp v60, v61, v61 row_bcast:31 row_mask:0xc bank_mask:0xf
	s_nop 1
	v_readlane_b32 s16, v60, 63
	s_nop 1
	v_mov_b32_e32 v148, s16
	v_fmamk_f32 v148, v148, 0x3a800000, v66
	v_rsq_f32_e32 v148, v148
	s_nop 0
	s_waitcnt vmcnt(4)
	v_pk_mul_f32 v[68:69], v[68:69], v[148:149] op_sel_hi:[1,0]
	v_pk_mul_f32 v[70:71], v[70:71], v[148:149] op_sel_hi:[1,0]
	v_pk_add_f32 v[116:117], v[116:117], 1.0 op_sel_hi:[1,0]
	v_pk_add_f32 v[118:119], v[118:119], 1.0 op_sel_hi:[1,0]
	v_pk_mul_f32 v[68:69], v[0:1], v[68:69]
	v_pk_mul_f32 v[70:71], v[2:3], v[70:71]
	v_pk_fma_f32 v[68:69], v[68:69], v[116:117], v[132:133]
	v_pk_fma_f32 v[70:71], v[70:71], v[118:119], v[134:135]
	v_cvt_pk_bf16_f32 v68, v68, v69
	v_cvt_pk_bf16_f32 v69, v70, v71
	global_store_dwordx2 v48, v[68:69], s[14:15]
	v_pk_mul_f32 v[72:73], v[72:73], v[148:149] op_sel_hi:[1,0]
	v_pk_mul_f32 v[74:75], v[74:75], v[148:149] op_sel_hi:[1,0]
	v_pk_add_f32 v[120:121], v[120:121], 1.0 op_sel_hi:[1,0]
	v_pk_add_f32 v[122:123], v[122:123], 1.0 op_sel_hi:[1,0]
	v_pk_mul_f32 v[72:73], v[4:5], v[72:73]
	v_pk_mul_f32 v[74:75], v[6:7], v[74:75]
	v_pk_fma_f32 v[72:73], v[72:73], v[120:121], v[136:137]
	v_pk_fma_f32 v[74:75], v[74:75], v[122:123], v[138:139]
	v_cvt_pk_bf16_f32 v72, v72, v73
	v_cvt_pk_bf16_f32 v73, v74, v75
	global_store_dwordx2 v48, v[72:73], s[14:15] offset:512
	v_pk_mul_f32 v[76:77], v[76:77], v[148:149] op_sel_hi:[1,0]
	v_pk_mul_f32 v[78:79], v[78:79], v[148:149] op_sel_hi:[1,0]
	v_pk_add_f32 v[124:125], v[124:125], 1.0 op_sel_hi:[1,0]
	v_pk_add_f32 v[126:127], v[126:127], 1.0 op_sel_hi:[1,0]
	v_pk_mul_f32 v[76:77], v[8:9], v[76:77]
	v_pk_mul_f32 v[78:79], v[10:11], v[78:79]
	v_pk_fma_f32 v[76:77], v[76:77], v[124:125], v[140:141]
	v_pk_fma_f32 v[78:79], v[78:79], v[126:127], v[142:143]
	v_cvt_pk_bf16_f32 v76, v76, v77
	v_cvt_pk_bf16_f32 v77, v78, v79
	global_store_dwordx2 v48, v[76:77], s[14:15] offset:1024
	v_pk_mul_f32 v[80:81], v[80:81], v[148:149] op_sel_hi:[1,0]
	v_pk_mul_f32 v[82:83], v[82:83], v[148:149] op_sel_hi:[1,0]
	v_pk_add_f32 v[128:129], v[128:129], 1.0 op_sel_hi:[1,0]
	v_pk_add_f32 v[130:131], v[130:131], 1.0 op_sel_hi:[1,0]
	v_pk_mul_f32 v[80:81], v[12:13], v[80:81]
	v_pk_mul_f32 v[82:83], v[14:15], v[82:83]
	v_pk_fma_f32 v[80:81], v[80:81], v[128:129], v[144:145]
	v_pk_fma_f32 v[82:83], v[82:83], v[130:131], v[146:147]
	v_cvt_pk_bf16_f32 v80, v80, v81
	v_cvt_pk_bf16_f32 v81, v82, v83
	global_store_dwordx2 v48, v[80:81], s[14:15] offset:1536
	s_cmp_eq_u32 s101, 2
	s_cbranch_scc1 .Lp1_done

.LBB0_135:
	s_cmp_eq_u32 s101, 1
	s_cbranch_scc0 .Lp1_done
	s_mov_b32 s101, 2
	s_branch .Lp1_norm
